# v19 plus: removed the 32 back-to-back s_setprio 0 / s_setprio 1 pairs in the middle of MFMA blocks (priority state unchanged)
# baseline (speedup 1.0000x reference)
.Lzacc0a:
	s_waitcnt vmcnt(8)
	s_waitcnt lgkmcnt(0)
	s_barrier
	s_setprio 1
	s_waitcnt lgkmcnt(0)
	v_mfma_f32_16x16x32_bf16 v[124:127], v[146:149], v[188:191], v[124:127]
	v_mfma_f32_16x16x32_bf16 v[120:123], v[164:167], v[188:191], v[120:123]
	v_mfma_f32_16x16x32_bf16 v[116:119], v[146:149], v[196:199], v[116:119]
	v_mfma_f32_16x16x32_bf16 v[112:115], v[164:167], v[196:199], v[112:115]
	v_mfma_f32_16x16x32_bf16 v[100:103], v[146:149], v[204:207], v[100:103]
	v_mfma_f32_16x16x32_bf16 v[96:99], v[164:167], v[204:207], v[96:99]
	v_mfma_f32_16x16x32_bf16 v[84:87], v[146:149], v[212:215], v[84:87]
	v_mfma_f32_16x16x32_bf16 v[80:83], v[164:167], v[212:215], v[80:83]
	v_mfma_f32_16x16x32_bf16 v[124:127], v[150:153], v[192:195], v[124:127]
	v_mfma_f32_16x16x32_bf16 v[120:123], v[168:171], v[192:195], v[120:123]
	v_mfma_f32_16x16x32_bf16 v[116:119], v[150:153], v[200:203], v[116:119]
	v_mfma_f32_16x16x32_bf16 v[112:115], v[168:171], v[200:203], v[112:115]
	v_mfma_f32_16x16x32_bf16 v[100:103], v[150:153], v[208:211], v[100:103]
	v_mfma_f32_16x16x32_bf16 v[96:99], v[168:171], v[208:211], v[96:99]
	v_mfma_f32_16x16x32_bf16 v[84:87], v[150:153], v[218:221], v[84:87]
	v_mfma_f32_16x16x32_bf16 v[80:83], v[168:171], v[218:221], v[80:83]
	v_mfma_f32_16x16x32_bf16 v[108:111], v[172:175], v[188:191], v[108:111]
	v_mfma_f32_16x16x32_bf16 v[104:107], v[180:183], v[188:191], v[104:107]
	v_mfma_f32_16x16x32_bf16 v[92:95], v[172:175], v[196:199], v[92:95]
	v_mfma_f32_16x16x32_bf16 v[88:91], v[180:183], v[196:199], v[88:91]
	v_mfma_f32_16x16x32_bf16 v[76:79], v[172:175], v[204:207], v[76:79]
	v_mfma_f32_16x16x32_bf16 v[72:75], v[180:183], v[204:207], v[72:75]
	v_mfma_f32_16x16x32_bf16 v[68:71], v[172:175], v[212:215], v[68:71]
	v_mfma_f32_16x16x32_bf16 v[64:67], v[180:183], v[212:215], v[64:67]
	v_mfma_f32_16x16x32_bf16 v[108:111], v[176:179], v[192:195], v[108:111]
	v_mfma_f32_16x16x32_bf16 v[104:107], v[184:187], v[192:195], v[104:107]
	v_mfma_f32_16x16x32_bf16 v[92:95], v[176:179], v[200:203], v[92:95]
	v_mfma_f32_16x16x32_bf16 v[88:91], v[184:187], v[200:203], v[88:91]
	v_mfma_f32_16x16x32_bf16 v[76:79], v[176:179], v[208:211], v[76:79]
	v_mfma_f32_16x16x32_bf16 v[72:75], v[184:187], v[208:211], v[72:75]
	v_mfma_f32_16x16x32_bf16 v[68:71], v[176:179], v[218:221], v[68:71]
	v_mfma_f32_16x16x32_bf16 v[64:67], v[184:187], v[218:221], v[64:67]
	s_setprio 0
	s_barrier
	s_add_i32 s79, s64, s58
	v_lshl_add_u64 v[154:155], s[50:51], 0, v[132:133]
	s_mov_b32 m0, s79
	ds_read_b128 v[188:191], v162 offset:16384
	ds_read_b128 v[192:195], v162 offset:17408
	ds_read_b128 v[196:199], v162 offset:18432
	ds_read_b128 v[200:203], v162 offset:19456
	ds_read_b128 v[204:207], v162 offset:20480
	ds_read_b128 v[208:211], v162 offset:21504
	ds_read_b128 v[212:215], v162 offset:22528
	ds_read_b128 v[218:221], v162 offset:23552
	global_load_lds_dwordx4 v[154:155], off
	s_add_i32 m0, s79, 0x2000
	s_add_u32 s80, s50, 0x40000
	v_lshl_add_u64 v[222:223], s[50:51], 0, v[128:129]
	s_addc_u32 s81, s51, 0
	s_add_i32 s79, s65, s58
	global_load_lds_dwordx4 v[222:223], off
	v_lshl_add_u64 v[224:225], s[80:81], 0, v[132:133]
	s_mov_b32 m0, s79
	v_lshl_add_u64 v[226:227], s[52:53], 0, v[130:131]
	global_load_lds_dwordx4 v[224:225], off
	v_lshl_add_u64 v[224:225], s[80:81], 0, v[128:129]
	s_add_i32 m0, s79, 0x2000
	s_nop 0
	global_load_lds_dwordx4 v[224:225], off
	v_lshl_add_u64 v[224:225], s[52:53], 0, v[134:135]
	s_mov_b32 m0, s6
	s_nop 0
	global_load_lds_dwordx4 v[224:225], off
	s_mov_b32 m0, s21
	s_nop 0
	global_load_lds_dwordx4 v[226:227], off
	s_cmp_lg_u32 s78, -2
	s_cbranch_scc1 .Lzacc0b
	v_mov_b32_e32 v0, 0
	v_mov_b32_e32 v1, 0
	v_mov_b32_e32 v2, 0
	v_mov_b32_e32 v3, 0
	v_mov_b32_e32 v4, 0
	v_mov_b32_e32 v5, 0
	v_mov_b32_e32 v6, 0
	v_mov_b32_e32 v7, 0
	v_mov_b32_e32 v8, 0
	v_mov_b32_e32 v9, 0
	v_mov_b32_e32 v10, 0
	v_mov_b32_e32 v11, 0
	v_mov_b32_e32 v12, 0
	v_mov_b32_e32 v13, 0
	v_mov_b32_e32 v14, 0
	v_mov_b32_e32 v15, 0
	v_mov_b32_e32 v16, 0
	v_mov_b32_e32 v17, 0
	v_mov_b32_e32 v18, 0
	v_mov_b32_e32 v19, 0
	v_mov_b32_e32 v20, 0
	v_mov_b32_e32 v21, 0
	v_mov_b32_e32 v22, 0
	v_mov_b32_e32 v23, 0
	v_mov_b32_e32 v24, 0
	v_mov_b32_e32 v25, 0
	v_mov_b32_e32 v26, 0
	v_mov_b32_e32 v27, 0
	v_mov_b32_e32 v28, 0
	v_mov_b32_e32 v29, 0
	v_mov_b32_e32 v30, 0
	v_mov_b32_e32 v31, 0
	v_mov_b32_e32 v32, 0
	v_mov_b32_e32 v33, 0
	v_mov_b32_e32 v34, 0
	v_mov_b32_e32 v35, 0
	v_mov_b32_e32 v36, 0
	v_mov_b32_e32 v37, 0
	v_mov_b32_e32 v38, 0
	v_mov_b32_e32 v39, 0
	v_mov_b32_e32 v40, 0
	v_mov_b32_e32 v41, 0
	v_mov_b32_e32 v42, 0
	v_mov_b32_e32 v43, 0
	v_mov_b32_e32 v44, 0
	v_mov_b32_e32 v45, 0
	v_mov_b32_e32 v46, 0
	v_mov_b32_e32 v47, 0
	v_mov_b32_e32 v48, 0
	v_mov_b32_e32 v49, 0
	v_mov_b32_e32 v50, 0
	v_mov_b32_e32 v51, 0
	v_mov_b32_e32 v52, 0
	v_mov_b32_e32 v53, 0
	v_mov_b32_e32 v54, 0
	v_mov_b32_e32 v55, 0
	v_mov_b32_e32 v56, 0
	v_mov_b32_e32 v57, 0
	v_mov_b32_e32 v58, 0
	v_mov_b32_e32 v59, 0
	v_mov_b32_e32 v60, 0
	v_mov_b32_e32 v61, 0
	v_mov_b32_e32 v62, 0
	v_mov_b32_e32 v63, 0
.Lzacc0b:
	s_waitcnt vmcnt(8)
	s_waitcnt lgkmcnt(0)
	s_barrier
	s_setprio 1
	s_waitcnt lgkmcnt(0)
	v_mfma_f32_16x16x32_bf16 v[60:63], v[146:149], v[188:191], v[60:63]
	v_mfma_f32_16x16x32_bf16 v[56:59], v[164:167], v[188:191], v[56:59]
	v_mfma_f32_16x16x32_bf16 v[52:55], v[146:149], v[196:199], v[52:55]
	v_mfma_f32_16x16x32_bf16 v[48:51], v[164:167], v[196:199], v[48:51]
	v_mfma_f32_16x16x32_bf16 v[36:39], v[146:149], v[204:207], v[36:39]
	v_mfma_f32_16x16x32_bf16 v[32:35], v[164:167], v[204:207], v[32:35]
	v_mfma_f32_16x16x32_bf16 v[20:23], v[146:149], v[212:215], v[20:23]
	v_mfma_f32_16x16x32_bf16 v[16:19], v[164:167], v[212:215], v[16:19]
	v_mfma_f32_16x16x32_bf16 v[60:63], v[150:153], v[192:195], v[60:63]
	v_mfma_f32_16x16x32_bf16 v[56:59], v[168:171], v[192:195], v[56:59]
	v_mfma_f32_16x16x32_bf16 v[52:55], v[150:153], v[200:203], v[52:55]
	v_mfma_f32_16x16x32_bf16 v[48:51], v[168:171], v[200:203], v[48:51]
	v_mfma_f32_16x16x32_bf16 v[36:39], v[150:153], v[208:211], v[36:39]
	v_mfma_f32_16x16x32_bf16 v[32:35], v[168:171], v[208:211], v[32:35]
	v_mfma_f32_16x16x32_bf16 v[20:23], v[150:153], v[218:221], v[20:23]
	v_mfma_f32_16x16x32_bf16 v[16:19], v[168:171], v[218:221], v[16:19]
	v_mfma_f32_16x16x32_bf16 v[44:47], v[172:175], v[188:191], v[44:47]
	v_mfma_f32_16x16x32_bf16 v[40:43], v[180:183], v[188:191], v[40:43]
	v_mfma_f32_16x16x32_bf16 v[28:31], v[172:175], v[196:199], v[28:31]
	v_mfma_f32_16x16x32_bf16 v[24:27], v[180:183], v[196:199], v[24:27]
	v_mfma_f32_16x16x32_bf16 v[12:15], v[172:175], v[204:207], v[12:15]
	v_mfma_f32_16x16x32_bf16 v[8:11], v[180:183], v[204:207], v[8:11]
	v_mfma_f32_16x16x32_bf16 v[4:7], v[172:175], v[212:215], v[4:7]
	v_mfma_f32_16x16x32_bf16 v[0:3], v[180:183], v[212:215], v[0:3]
	v_mfma_f32_16x16x32_bf16 v[44:47], v[176:179], v[192:195], v[44:47]
	v_mfma_f32_16x16x32_bf16 v[40:43], v[184:187], v[192:195], v[40:43]
	v_mfma_f32_16x16x32_bf16 v[28:31], v[176:179], v[200:203], v[28:31]
	v_mfma_f32_16x16x32_bf16 v[24:27], v[184:187], v[200:203], v[24:27]
	v_mfma_f32_16x16x32_bf16 v[12:15], v[176:179], v[208:211], v[12:15]
	v_mfma_f32_16x16x32_bf16 v[8:11], v[184:187], v[208:211], v[8:11]
	v_mfma_f32_16x16x32_bf16 v[4:7], v[176:179], v[218:221], v[4:7]
	v_mfma_f32_16x16x32_bf16 v[0:3], v[184:187], v[218:221], v[0:3]
	s_setprio 0
	s_barrier
	s_add_i32 s79, 0, 0x18000
	v_add_u32_e32 v136, s79, v157
	s_add_i32 s80, 0, 0x1c000
	ds_read_b128 v[146:149], v136
	ds_read_b128 v[150:153], v136 offset:1024
	ds_read_b128 v[164:167], v136 offset:2048
	ds_read_b128 v[168:171], v136 offset:3072
	v_add_u32_e32 v136, s80, v157
	ds_read_b128 v[172:175], v136
	ds_read_b128 v[176:179], v136 offset:1024
	ds_read_b128 v[180:183], v136 offset:2048
	ds_read_b128 v[184:187], v136 offset:3072
	s_add_u32 s52, s52, 0x40000
	s_addc_u32 s53, s53, 0
	s_mov_b32 m0, s59
	v_lshl_add_u64 v[228:229], s[52:53], 0, v[134:135]
	ds_read_b128 v[188:191], v162 offset:32768
	ds_read_b128 v[192:195], v162 offset:33792
	ds_read_b128 v[196:199], v162 offset:34816
	ds_read_b128 v[200:203], v162 offset:35840
	ds_read_b128 v[204:207], v162 offset:36864
	ds_read_b128 v[208:211], v162 offset:37888
	ds_read_b128 v[212:215], v162 offset:38912
	ds_read_b128 v[218:221], v162 offset:39936
	global_load_lds_dwordx4 v[228:229], off
	v_lshl_add_u64 v[228:229], s[52:53], 0, v[130:131]
	s_mov_b32 m0, s60
	s_nop 0
	global_load_lds_dwordx4 v[228:229], off
	s_waitcnt vmcnt(8)
	s_waitcnt lgkmcnt(0)
	s_barrier
	s_setprio 1
	s_waitcnt lgkmcnt(0)
	v_mfma_f32_16x16x32_bf16 v[124:127], v[146:149], v[188:191], v[124:127]
	v_mfma_f32_16x16x32_bf16 v[120:123], v[164:167], v[188:191], v[120:123]
	v_mfma_f32_16x16x32_bf16 v[116:119], v[146:149], v[196:199], v[116:119]
	v_mfma_f32_16x16x32_bf16 v[112:115], v[164:167], v[196:199], v[112:115]
	v_mfma_f32_16x16x32_bf16 v[100:103], v[146:149], v[204:207], v[100:103]
	v_mfma_f32_16x16x32_bf16 v[96:99], v[164:167], v[204:207], v[96:99]
	v_mfma_f32_16x16x32_bf16 v[84:87], v[146:149], v[212:215], v[84:87]
	v_mfma_f32_16x16x32_bf16 v[80:83], v[164:167], v[212:215], v[80:83]
	v_mfma_f32_16x16x32_bf16 v[124:127], v[150:153], v[192:195], v[124:127]
	v_mfma_f32_16x16x32_bf16 v[120:123], v[168:171], v[192:195], v[120:123]
	v_mfma_f32_16x16x32_bf16 v[116:119], v[150:153], v[200:203], v[116:119]
	v_mfma_f32_16x16x32_bf16 v[112:115], v[168:171], v[200:203], v[112:115]
	v_mfma_f32_16x16x32_bf16 v[100:103], v[150:153], v[208:211], v[100:103]
	v_mfma_f32_16x16x32_bf16 v[96:99], v[168:171], v[208:211], v[96:99]
	v_mfma_f32_16x16x32_bf16 v[84:87], v[150:153], v[218:221], v[84:87]
	v_mfma_f32_16x16x32_bf16 v[80:83], v[168:171], v[218:221], v[80:83]
	v_mfma_f32_16x16x32_bf16 v[108:111], v[172:175], v[188:191], v[108:111]
	v_mfma_f32_16x16x32_bf16 v[104:107], v[180:183], v[188:191], v[104:107]
	v_mfma_f32_16x16x32_bf16 v[92:95], v[172:175], v[196:199], v[92:95]
	v_mfma_f32_16x16x32_bf16 v[88:91], v[180:183], v[196:199], v[88:91]
	v_mfma_f32_16x16x32_bf16 v[76:79], v[172:175], v[204:207], v[76:79]
	v_mfma_f32_16x16x32_bf16 v[72:75], v[180:183], v[204:207], v[72:75]
	v_mfma_f32_16x16x32_bf16 v[68:71], v[172:175], v[212:215], v[68:71]
	v_mfma_f32_16x16x32_bf16 v[64:67], v[180:183], v[212:215], v[64:67]
	v_mfma_f32_16x16x32_bf16 v[108:111], v[176:179], v[192:195], v[108:111]
	v_mfma_f32_16x16x32_bf16 v[104:107], v[184:187], v[192:195], v[104:107]
	v_mfma_f32_16x16x32_bf16 v[92:95], v[176:179], v[200:203], v[92:95]
	v_mfma_f32_16x16x32_bf16 v[88:91], v[184:187], v[200:203], v[88:91]
	v_mfma_f32_16x16x32_bf16 v[76:79], v[176:179], v[208:211], v[76:79]
	v_mfma_f32_16x16x32_bf16 v[72:75], v[184:187], v[208:211], v[72:75]
	v_mfma_f32_16x16x32_bf16 v[68:71], v[176:179], v[218:221], v[68:71]
	v_mfma_f32_16x16x32_bf16 v[64:67], v[184:187], v[218:221], v[64:67]
	s_setprio 0
	s_barrier
	s_add_i32 s52, s79, s58
	v_lshl_add_u64 v[154:155], v[154:155], 0, s[16:17]
	s_mov_b32 m0, s52
	ds_read_b128 v[188:191], v162 offset:49152
	ds_read_b128 v[192:195], v162 offset:50176
	ds_read_b128 v[196:199], v162 offset:51200
	ds_read_b128 v[200:203], v162 offset:52224
	ds_read_b128 v[204:207], v162 offset:53248
	ds_read_b128 v[208:211], v162 offset:54272
	ds_read_b128 v[212:215], v162 offset:55296
	ds_read_b128 v[218:221], v162 offset:56320
	global_load_lds_dwordx4 v[154:155], off
	s_add_i32 m0, s52, 0x2000
	s_add_u32 s50, s50, 0x40080
	v_lshl_add_u64 v[154:155], v[222:223], 0, s[16:17]
	s_addc_u32 s51, s51, 0
	s_add_i32 s52, s80, s58
	global_load_lds_dwordx4 v[154:155], off
	v_lshl_add_u64 v[154:155], s[50:51], 0, v[132:133]
	s_mov_b32 m0, s52
	s_nop 0
	global_load_lds_dwordx4 v[154:155], off
	v_lshl_add_u64 v[154:155], s[50:51], 0, v[128:129]
	s_add_i32 m0, s52, 0x2000
	s_nop 0
	global_load_lds_dwordx4 v[154:155], off
	v_lshl_add_u64 v[154:155], v[224:225], 0, s[16:17]
	s_mov_b32 m0, s61
	s_nop 0
	global_load_lds_dwordx4 v[154:155], off
	v_lshl_add_u64 v[154:155], v[226:227], 0, s[16:17]
	s_mov_b32 m0, s62
	s_nop 0
	global_load_lds_dwordx4 v[154:155], off
	s_waitcnt vmcnt(8)
	s_waitcnt lgkmcnt(0)
	s_barrier
	s_setprio 1
	s_waitcnt lgkmcnt(0)
	v_mfma_f32_16x16x32_bf16 v[60:63], v[146:149], v[188:191], v[60:63]
	v_mfma_f32_16x16x32_bf16 v[56:59], v[164:167], v[188:191], v[56:59]
	v_mfma_f32_16x16x32_bf16 v[52:55], v[146:149], v[196:199], v[52:55]
	v_mfma_f32_16x16x32_bf16 v[48:51], v[164:167], v[196:199], v[48:51]
	v_mfma_f32_16x16x32_bf16 v[36:39], v[146:149], v[204:207], v[36:39]
	v_mfma_f32_16x16x32_bf16 v[32:35], v[164:167], v[204:207], v[32:35]
	v_mfma_f32_16x16x32_bf16 v[20:23], v[146:149], v[212:215], v[20:23]
	v_mfma_f32_16x16x32_bf16 v[16:19], v[164:167], v[212:215], v[16:19]
	v_mfma_f32_16x16x32_bf16 v[60:63], v[150:153], v[192:195], v[60:63]
	v_mfma_f32_16x16x32_bf16 v[56:59], v[168:171], v[192:195], v[56:59]
	v_mfma_f32_16x16x32_bf16 v[52:55], v[150:153], v[200:203], v[52:55]
	v_mfma_f32_16x16x32_bf16 v[48:51], v[168:171], v[200:203], v[48:51]
	v_mfma_f32_16x16x32_bf16 v[36:39], v[150:153], v[208:211], v[36:39]
	v_mfma_f32_16x16x32_bf16 v[32:35], v[168:171], v[208:211], v[32:35]
	v_mfma_f32_16x16x32_bf16 v[20:23], v[150:153], v[218:221], v[20:23]
	v_mfma_f32_16x16x32_bf16 v[16:19], v[168:171], v[218:221], v[16:19]
	v_mfma_f32_16x16x32_bf16 v[44:47], v[172:175], v[188:191], v[44:47]
	v_mfma_f32_16x16x32_bf16 v[40:43], v[180:183], v[188:191], v[40:43]
	v_mfma_f32_16x16x32_bf16 v[28:31], v[172:175], v[196:199], v[28:31]
	v_mfma_f32_16x16x32_bf16 v[24:27], v[180:183], v[196:199], v[24:27]
	v_mfma_f32_16x16x32_bf16 v[12:15], v[172:175], v[204:207], v[12:15]
	v_mfma_f32_16x16x32_bf16 v[8:11], v[180:183], v[204:207], v[8:11]
	v_mfma_f32_16x16x32_bf16 v[4:7], v[172:175], v[212:215], v[4:7]
	v_mfma_f32_16x16x32_bf16 v[0:3], v[180:183], v[212:215], v[0:3]
	v_mfma_f32_16x16x32_bf16 v[44:47], v[176:179], v[192:195], v[44:47]
	v_mfma_f32_16x16x32_bf16 v[40:43], v[184:187], v[192:195], v[40:43]
	v_mfma_f32_16x16x32_bf16 v[28:31], v[176:179], v[200:203], v[28:31]
	v_mfma_f32_16x16x32_bf16 v[24:27], v[184:187], v[200:203], v[24:27]
	v_mfma_f32_16x16x32_bf16 v[12:15], v[176:179], v[208:211], v[12:15]
	v_mfma_f32_16x16x32_bf16 v[8:11], v[184:187], v[208:211], v[8:11]
	v_mfma_f32_16x16x32_bf16 v[4:7], v[176:179], v[218:221], v[4:7]
	v_mfma_f32_16x16x32_bf16 v[0:3], v[184:187], v[218:221], v[0:3]
	s_setprio 0
	s_barrier
	s_add_i32 s78, s78, 2
	s_add_u32 s48, s48, 0x100
	s_addc_u32 s49, s49, 0
	s_add_u32 s76, s76, 0x100
	s_addc_u32 s77, s77, 0
	s_cmp_gt_u32 s78, 13
	s_cbranch_scc0 .LBB0_158
	s_and_b64 vcc, exec, s[18:19]
	s_cbranch_vccz .LBB0_161
	s_barrier

.Lzacc1a:
	s_waitcnt vmcnt(8)
	s_waitcnt lgkmcnt(0)
	s_barrier
	s_setprio 1
	s_waitcnt lgkmcnt(0)
	v_mfma_f32_16x16x32_bf16 v[124:127], v[128:131], v[160:163], v[124:127]
	v_mfma_f32_16x16x32_bf16 v[120:123], v[136:139], v[160:163], v[120:123]
	v_mfma_f32_16x16x32_bf16 v[108:111], v[128:131], v[168:171], v[108:111]
	v_mfma_f32_16x16x32_bf16 v[104:107], v[136:139], v[168:171], v[104:107]
	v_mfma_f32_16x16x32_bf16 v[92:95], v[128:131], v[192:195], v[92:95]
	v_mfma_f32_16x16x32_bf16 v[88:91], v[136:139], v[192:195], v[88:91]
	v_mfma_f32_16x16x32_bf16 v[76:79], v[128:131], v[200:203], v[76:79]
	v_mfma_f32_16x16x32_bf16 v[72:75], v[136:139], v[200:203], v[72:75]
	v_mfma_f32_16x16x32_bf16 v[124:127], v[132:135], v[164:167], v[124:127]
	v_mfma_f32_16x16x32_bf16 v[120:123], v[140:143], v[164:167], v[120:123]
	v_mfma_f32_16x16x32_bf16 v[108:111], v[132:135], v[172:175], v[108:111]
	v_mfma_f32_16x16x32_bf16 v[104:107], v[140:143], v[172:175], v[104:107]
	v_mfma_f32_16x16x32_bf16 v[92:95], v[132:135], v[196:199], v[92:95]
	v_mfma_f32_16x16x32_bf16 v[88:91], v[140:143], v[196:199], v[88:91]
	v_mfma_f32_16x16x32_bf16 v[76:79], v[132:135], v[218:221], v[76:79]
	v_mfma_f32_16x16x32_bf16 v[72:75], v[140:143], v[218:221], v[72:75]
	v_mfma_f32_16x16x32_bf16 v[116:119], v[144:147], v[160:163], v[116:119]
	v_mfma_f32_16x16x32_bf16 v[112:115], v[152:155], v[160:163], v[112:115]
	v_mfma_f32_16x16x32_bf16 v[100:103], v[144:147], v[168:171], v[100:103]
	v_mfma_f32_16x16x32_bf16 v[96:99], v[152:155], v[168:171], v[96:99]
	v_mfma_f32_16x16x32_bf16 v[84:87], v[144:147], v[192:195], v[84:87]
	v_mfma_f32_16x16x32_bf16 v[80:83], v[152:155], v[192:195], v[80:83]
	v_mfma_f32_16x16x32_bf16 v[68:71], v[144:147], v[200:203], v[68:71]
	v_mfma_f32_16x16x32_bf16 v[64:67], v[152:155], v[200:203], v[64:67]
	v_mfma_f32_16x16x32_bf16 v[116:119], v[148:151], v[164:167], v[116:119]
	v_mfma_f32_16x16x32_bf16 v[112:115], v[156:159], v[164:167], v[112:115]
	v_mfma_f32_16x16x32_bf16 v[100:103], v[148:151], v[172:175], v[100:103]
	v_mfma_f32_16x16x32_bf16 v[96:99], v[156:159], v[172:175], v[96:99]
	v_mfma_f32_16x16x32_bf16 v[84:87], v[148:151], v[196:199], v[84:87]
	v_mfma_f32_16x16x32_bf16 v[80:83], v[156:159], v[196:199], v[80:83]
	v_mfma_f32_16x16x32_bf16 v[68:71], v[148:151], v[218:221], v[68:71]
	v_mfma_f32_16x16x32_bf16 v[64:67], v[156:159], v[218:221], v[64:67]
	s_setprio 0
	s_barrier
	s_add_i32 s77, s72, s61
	v_lshl_add_u64 v[214:215], s[54:55], 0, v[178:179]
	s_mov_b32 m0, s77
	ds_read_b128 v[160:163], v211 offset:16384
	ds_read_b128 v[164:167], v211 offset:17408
	ds_read_b128 v[168:171], v211 offset:18432
	ds_read_b128 v[172:175], v211 offset:19456
	ds_read_b128 v[192:195], v211 offset:20480
	ds_read_b128 v[196:199], v211 offset:21504
	ds_read_b128 v[200:203], v211 offset:22528
	ds_read_b128 v[218:221], v211 offset:23552
	global_load_lds_dwordx4 v[214:215], off
	s_add_i32 m0, s77, 0x2000
	s_add_u32 s78, s54, 0x40000
	v_lshl_add_u64 v[222:223], s[54:55], 0, v[182:183]
	s_addc_u32 s79, s55, 0
	s_add_i32 s77, s73, s61
	global_load_lds_dwordx4 v[222:223], off
	v_lshl_add_u64 v[224:225], s[78:79], 0, v[178:179]
	s_mov_b32 m0, s77
	v_lshl_add_u64 v[226:227], s[56:57], 0, v[180:181]
	global_load_lds_dwordx4 v[224:225], off
	v_lshl_add_u64 v[224:225], s[78:79], 0, v[182:183]
	s_add_i32 m0, s77, 0x2000
	s_nop 0
	global_load_lds_dwordx4 v[224:225], off
	v_lshl_add_u64 v[224:225], s[56:57], 0, v[176:177]
	s_mov_b32 m0, s62
	s_nop 0
	global_load_lds_dwordx4 v[224:225], off
	s_mov_b32 m0, s63
	s_nop 0
	global_load_lds_dwordx4 v[226:227], off
	s_cmp_lg_u32 s76, -2
	s_cbranch_scc1 .Lzacc1b
	v_mov_b32_e32 v0, 0
	v_mov_b32_e32 v1, 0
	v_mov_b32_e32 v2, 0
	v_mov_b32_e32 v3, 0
	v_mov_b32_e32 v4, 0
	v_mov_b32_e32 v5, 0
	v_mov_b32_e32 v6, 0
	v_mov_b32_e32 v7, 0
	v_mov_b32_e32 v8, 0
	v_mov_b32_e32 v9, 0
	v_mov_b32_e32 v10, 0
	v_mov_b32_e32 v11, 0
	v_mov_b32_e32 v12, 0
	v_mov_b32_e32 v13, 0
	v_mov_b32_e32 v14, 0
	v_mov_b32_e32 v15, 0
	v_mov_b32_e32 v16, 0
	v_mov_b32_e32 v17, 0
	v_mov_b32_e32 v18, 0
	v_mov_b32_e32 v19, 0
	v_mov_b32_e32 v20, 0
	v_mov_b32_e32 v21, 0
	v_mov_b32_e32 v22, 0
	v_mov_b32_e32 v23, 0
	v_mov_b32_e32 v24, 0
	v_mov_b32_e32 v25, 0
	v_mov_b32_e32 v26, 0
	v_mov_b32_e32 v27, 0
	v_mov_b32_e32 v28, 0
	v_mov_b32_e32 v29, 0
	v_mov_b32_e32 v30, 0
	v_mov_b32_e32 v31, 0
	v_mov_b32_e32 v32, 0
	v_mov_b32_e32 v33, 0
	v_mov_b32_e32 v34, 0
	v_mov_b32_e32 v35, 0
	v_mov_b32_e32 v36, 0
	v_mov_b32_e32 v37, 0
	v_mov_b32_e32 v38, 0
	v_mov_b32_e32 v39, 0
	v_mov_b32_e32 v40, 0
	v_mov_b32_e32 v41, 0
	v_mov_b32_e32 v42, 0
	v_mov_b32_e32 v43, 0
	v_mov_b32_e32 v44, 0
	v_mov_b32_e32 v45, 0
	v_mov_b32_e32 v46, 0
	v_mov_b32_e32 v47, 0
	v_mov_b32_e32 v48, 0
	v_mov_b32_e32 v49, 0
	v_mov_b32_e32 v50, 0
	v_mov_b32_e32 v51, 0
	v_mov_b32_e32 v52, 0
	v_mov_b32_e32 v53, 0
	v_mov_b32_e32 v54, 0
	v_mov_b32_e32 v55, 0
	v_mov_b32_e32 v56, 0
	v_mov_b32_e32 v57, 0
	v_mov_b32_e32 v58, 0
	v_mov_b32_e32 v59, 0
	v_mov_b32_e32 v60, 0
	v_mov_b32_e32 v61, 0
	v_mov_b32_e32 v62, 0
	v_mov_b32_e32 v63, 0
.Lzacc1b:
	s_waitcnt vmcnt(8)
	s_waitcnt lgkmcnt(0)
	s_barrier
	s_setprio 1
	s_waitcnt lgkmcnt(0)
	v_mfma_f32_16x16x32_bf16 v[60:63], v[128:131], v[160:163], v[60:63]
	v_mfma_f32_16x16x32_bf16 v[56:59], v[136:139], v[160:163], v[56:59]
	v_mfma_f32_16x16x32_bf16 v[44:47], v[128:131], v[168:171], v[44:47]
	v_mfma_f32_16x16x32_bf16 v[40:43], v[136:139], v[168:171], v[40:43]
	v_mfma_f32_16x16x32_bf16 v[28:31], v[128:131], v[192:195], v[28:31]
	v_mfma_f32_16x16x32_bf16 v[24:27], v[136:139], v[192:195], v[24:27]
	v_mfma_f32_16x16x32_bf16 v[12:15], v[128:131], v[200:203], v[12:15]
	v_mfma_f32_16x16x32_bf16 v[8:11], v[136:139], v[200:203], v[8:11]
	v_mfma_f32_16x16x32_bf16 v[60:63], v[132:135], v[164:167], v[60:63]
	v_mfma_f32_16x16x32_bf16 v[56:59], v[140:143], v[164:167], v[56:59]
	v_mfma_f32_16x16x32_bf16 v[44:47], v[132:135], v[172:175], v[44:47]
	v_mfma_f32_16x16x32_bf16 v[40:43], v[140:143], v[172:175], v[40:43]
	v_mfma_f32_16x16x32_bf16 v[28:31], v[132:135], v[196:199], v[28:31]
	v_mfma_f32_16x16x32_bf16 v[24:27], v[140:143], v[196:199], v[24:27]
	v_mfma_f32_16x16x32_bf16 v[12:15], v[132:135], v[218:221], v[12:15]
	v_mfma_f32_16x16x32_bf16 v[8:11], v[140:143], v[218:221], v[8:11]
	v_mfma_f32_16x16x32_bf16 v[52:55], v[144:147], v[160:163], v[52:55]
	v_mfma_f32_16x16x32_bf16 v[48:51], v[152:155], v[160:163], v[48:51]
	v_mfma_f32_16x16x32_bf16 v[36:39], v[144:147], v[168:171], v[36:39]
	v_mfma_f32_16x16x32_bf16 v[32:35], v[152:155], v[168:171], v[32:35]
	v_mfma_f32_16x16x32_bf16 v[20:23], v[144:147], v[192:195], v[20:23]
	v_mfma_f32_16x16x32_bf16 v[16:19], v[152:155], v[192:195], v[16:19]
	v_mfma_f32_16x16x32_bf16 v[4:7], v[144:147], v[200:203], v[4:7]
	v_mfma_f32_16x16x32_bf16 v[0:3], v[152:155], v[200:203], v[0:3]
	v_mfma_f32_16x16x32_bf16 v[52:55], v[148:151], v[164:167], v[52:55]
	v_mfma_f32_16x16x32_bf16 v[48:51], v[156:159], v[164:167], v[48:51]
	v_mfma_f32_16x16x32_bf16 v[36:39], v[148:151], v[172:175], v[36:39]
	v_mfma_f32_16x16x32_bf16 v[32:35], v[156:159], v[172:175], v[32:35]
	v_mfma_f32_16x16x32_bf16 v[20:23], v[148:151], v[196:199], v[20:23]
	v_mfma_f32_16x16x32_bf16 v[16:19], v[156:159], v[196:199], v[16:19]
	v_mfma_f32_16x16x32_bf16 v[4:7], v[148:151], v[218:221], v[4:7]
	v_mfma_f32_16x16x32_bf16 v[0:3], v[156:159], v[218:221], v[0:3]
	s_setprio 0
	s_barrier
	s_add_i32 s77, 0, 0x18000
	s_add_i32 s78, 0, 0x1c000
	v_add_u32_e32 v140, s77, v206
	v_add_u32_e32 v156, s78, v206
	ds_read_b128 v[128:131], v140
	ds_read_b128 v[132:135], v140 offset:1024
	ds_read_b128 v[136:139], v140 offset:2048
	ds_read_b128 v[140:143], v140 offset:3072
	ds_read_b128 v[144:147], v156
	ds_read_b128 v[148:151], v156 offset:1024
	ds_read_b128 v[152:155], v156 offset:2048
	ds_read_b128 v[156:159], v156 offset:3072
	s_add_u32 s56, s56, 0x40000
	s_addc_u32 s57, s57, 0
	s_mov_b32 m0, s64
	v_lshl_add_u64 v[228:229], s[56:57], 0, v[176:177]
	ds_read_b128 v[160:163], v211 offset:32768
	ds_read_b128 v[164:167], v211 offset:33792
	ds_read_b128 v[168:171], v211 offset:34816
	ds_read_b128 v[172:175], v211 offset:35840
	ds_read_b128 v[192:195], v211 offset:36864
	ds_read_b128 v[196:199], v211 offset:37888
	ds_read_b128 v[200:203], v211 offset:38912
	ds_read_b128 v[218:221], v211 offset:39936
	global_load_lds_dwordx4 v[228:229], off
	v_lshl_add_u64 v[228:229], s[56:57], 0, v[180:181]
	s_mov_b32 m0, s65
	s_nop 0
	global_load_lds_dwordx4 v[228:229], off
	s_waitcnt vmcnt(8)
	s_waitcnt lgkmcnt(0)
	s_barrier
	s_setprio 1
	s_waitcnt lgkmcnt(0)
	v_mfma_f32_16x16x32_bf16 v[124:127], v[128:131], v[160:163], v[124:127]
	v_mfma_f32_16x16x32_bf16 v[120:123], v[136:139], v[160:163], v[120:123]
	v_mfma_f32_16x16x32_bf16 v[108:111], v[128:131], v[168:171], v[108:111]
	v_mfma_f32_16x16x32_bf16 v[104:107], v[136:139], v[168:171], v[104:107]
	v_mfma_f32_16x16x32_bf16 v[92:95], v[128:131], v[192:195], v[92:95]
	v_mfma_f32_16x16x32_bf16 v[88:91], v[136:139], v[192:195], v[88:91]
	v_mfma_f32_16x16x32_bf16 v[76:79], v[128:131], v[200:203], v[76:79]
	v_mfma_f32_16x16x32_bf16 v[72:75], v[136:139], v[200:203], v[72:75]
	v_mfma_f32_16x16x32_bf16 v[124:127], v[132:135], v[164:167], v[124:127]
	v_mfma_f32_16x16x32_bf16 v[120:123], v[140:143], v[164:167], v[120:123]
	v_mfma_f32_16x16x32_bf16 v[108:111], v[132:135], v[172:175], v[108:111]
	v_mfma_f32_16x16x32_bf16 v[104:107], v[140:143], v[172:175], v[104:107]
	v_mfma_f32_16x16x32_bf16 v[92:95], v[132:135], v[196:199], v[92:95]
	v_mfma_f32_16x16x32_bf16 v[88:91], v[140:143], v[196:199], v[88:91]
	v_mfma_f32_16x16x32_bf16 v[76:79], v[132:135], v[218:221], v[76:79]
	v_mfma_f32_16x16x32_bf16 v[72:75], v[140:143], v[218:221], v[72:75]
	v_mfma_f32_16x16x32_bf16 v[116:119], v[144:147], v[160:163], v[116:119]
	v_mfma_f32_16x16x32_bf16 v[112:115], v[152:155], v[160:163], v[112:115]
	v_mfma_f32_16x16x32_bf16 v[100:103], v[144:147], v[168:171], v[100:103]
	v_mfma_f32_16x16x32_bf16 v[96:99], v[152:155], v[168:171], v[96:99]
	v_mfma_f32_16x16x32_bf16 v[84:87], v[144:147], v[192:195], v[84:87]
	v_mfma_f32_16x16x32_bf16 v[80:83], v[152:155], v[192:195], v[80:83]
	v_mfma_f32_16x16x32_bf16 v[68:71], v[144:147], v[200:203], v[68:71]
	v_mfma_f32_16x16x32_bf16 v[64:67], v[152:155], v[200:203], v[64:67]
	v_mfma_f32_16x16x32_bf16 v[116:119], v[148:151], v[164:167], v[116:119]
	v_mfma_f32_16x16x32_bf16 v[112:115], v[156:159], v[164:167], v[112:115]
	v_mfma_f32_16x16x32_bf16 v[100:103], v[148:151], v[172:175], v[100:103]
	v_mfma_f32_16x16x32_bf16 v[96:99], v[156:159], v[172:175], v[96:99]
	v_mfma_f32_16x16x32_bf16 v[84:87], v[148:151], v[196:199], v[84:87]
	v_mfma_f32_16x16x32_bf16 v[80:83], v[156:159], v[196:199], v[80:83]
	v_mfma_f32_16x16x32_bf16 v[68:71], v[148:151], v[218:221], v[68:71]
	v_mfma_f32_16x16x32_bf16 v[64:67], v[156:159], v[218:221], v[64:67]
	s_setprio 0
	s_barrier
	s_add_i32 s56, s77, s61
	v_lshl_add_u64 v[214:215], v[214:215], 0, s[26:27]
	s_mov_b32 m0, s56
	ds_read_b128 v[160:163], v211 offset:49152
	ds_read_b128 v[164:167], v211 offset:50176
	ds_read_b128 v[168:171], v211 offset:51200
	ds_read_b128 v[172:175], v211 offset:52224
	ds_read_b128 v[192:195], v211 offset:53248
	ds_read_b128 v[196:199], v211 offset:54272
	ds_read_b128 v[200:203], v211 offset:55296
	ds_read_b128 v[218:221], v211 offset:56320
	global_load_lds_dwordx4 v[214:215], off
	s_add_i32 m0, s56, 0x2000
	s_add_u32 s54, s54, 0x40080
	v_lshl_add_u64 v[214:215], v[222:223], 0, s[26:27]
	s_addc_u32 s55, s55, 0
	s_add_i32 s56, s78, s61
	global_load_lds_dwordx4 v[214:215], off
	v_lshl_add_u64 v[214:215], s[54:55], 0, v[178:179]
	s_mov_b32 m0, s56
	s_nop 0
	global_load_lds_dwordx4 v[214:215], off
	v_lshl_add_u64 v[214:215], s[54:55], 0, v[182:183]
	s_add_i32 m0, s56, 0x2000
	s_nop 0
	global_load_lds_dwordx4 v[214:215], off
	v_lshl_add_u64 v[214:215], v[224:225], 0, s[26:27]
	s_mov_b32 m0, s67
	s_nop 0
	global_load_lds_dwordx4 v[214:215], off
	v_lshl_add_u64 v[214:215], v[226:227], 0, s[26:27]
	s_mov_b32 m0, s68
	s_nop 0
	global_load_lds_dwordx4 v[214:215], off
	s_waitcnt vmcnt(8)
	s_waitcnt lgkmcnt(0)
	s_barrier
	s_setprio 1
	s_waitcnt lgkmcnt(0)
	v_mfma_f32_16x16x32_bf16 v[60:63], v[128:131], v[160:163], v[60:63]
	v_mfma_f32_16x16x32_bf16 v[56:59], v[136:139], v[160:163], v[56:59]
	v_mfma_f32_16x16x32_bf16 v[44:47], v[128:131], v[168:171], v[44:47]
	v_mfma_f32_16x16x32_bf16 v[40:43], v[136:139], v[168:171], v[40:43]
	v_mfma_f32_16x16x32_bf16 v[28:31], v[128:131], v[192:195], v[28:31]
	v_mfma_f32_16x16x32_bf16 v[24:27], v[136:139], v[192:195], v[24:27]
	v_mfma_f32_16x16x32_bf16 v[12:15], v[128:131], v[200:203], v[12:15]
	v_mfma_f32_16x16x32_bf16 v[8:11], v[136:139], v[200:203], v[8:11]
	v_mfma_f32_16x16x32_bf16 v[60:63], v[132:135], v[164:167], v[60:63]
	v_mfma_f32_16x16x32_bf16 v[56:59], v[140:143], v[164:167], v[56:59]
	v_mfma_f32_16x16x32_bf16 v[44:47], v[132:135], v[172:175], v[44:47]
	v_mfma_f32_16x16x32_bf16 v[40:43], v[140:143], v[172:175], v[40:43]
	v_mfma_f32_16x16x32_bf16 v[28:31], v[132:135], v[196:199], v[28:31]
	v_mfma_f32_16x16x32_bf16 v[24:27], v[140:143], v[196:199], v[24:27]
	v_mfma_f32_16x16x32_bf16 v[12:15], v[132:135], v[218:221], v[12:15]
	v_mfma_f32_16x16x32_bf16 v[8:11], v[140:143], v[218:221], v[8:11]
	v_mfma_f32_16x16x32_bf16 v[52:55], v[144:147], v[160:163], v[52:55]
	v_mfma_f32_16x16x32_bf16 v[48:51], v[152:155], v[160:163], v[48:51]
	v_mfma_f32_16x16x32_bf16 v[36:39], v[144:147], v[168:171], v[36:39]
	v_mfma_f32_16x16x32_bf16 v[32:35], v[152:155], v[168:171], v[32:35]
	v_mfma_f32_16x16x32_bf16 v[20:23], v[144:147], v[192:195], v[20:23]
	v_mfma_f32_16x16x32_bf16 v[16:19], v[152:155], v[192:195], v[16:19]
	v_mfma_f32_16x16x32_bf16 v[4:7], v[144:147], v[200:203], v[4:7]
	v_mfma_f32_16x16x32_bf16 v[0:3], v[152:155], v[200:203], v[0:3]
	v_mfma_f32_16x16x32_bf16 v[52:55], v[148:151], v[164:167], v[52:55]
	v_mfma_f32_16x16x32_bf16 v[48:51], v[156:159], v[164:167], v[48:51]
	v_mfma_f32_16x16x32_bf16 v[36:39], v[148:151], v[172:175], v[36:39]
	v_mfma_f32_16x16x32_bf16 v[32:35], v[156:159], v[172:175], v[32:35]
	v_mfma_f32_16x16x32_bf16 v[20:23], v[148:151], v[196:199], v[20:23]
	v_mfma_f32_16x16x32_bf16 v[16:19], v[156:159], v[196:199], v[16:19]
	v_mfma_f32_16x16x32_bf16 v[4:7], v[148:151], v[218:221], v[4:7]
	v_mfma_f32_16x16x32_bf16 v[0:3], v[156:159], v[218:221], v[0:3]
	s_setprio 0
	s_barrier
	s_add_i32 s76, s76, 2
	s_add_u32 s52, s52, 0x100
	s_addc_u32 s53, s53, 0
	s_add_u32 s51, s51, 0x100
	s_addc_u32 s75, s75, 0
	s_cmp_gt_u32 s76, 13
	s_cbranch_scc0 .LBB0_294
	s_and_b64 vcc, exec, s[28:29]
	s_cbranch_vccz .LBB0_297
	s_barrier

.Lzacc2a:
	s_waitcnt vmcnt(8)
	s_waitcnt lgkmcnt(0)
	s_barrier
	s_setprio 1
	s_waitcnt lgkmcnt(0)
	v_mfma_f32_16x16x32_bf16 v[124:127], v[128:131], v[160:163], v[124:127]
	v_mfma_f32_16x16x32_bf16 v[120:123], v[136:139], v[160:163], v[120:123]
	v_mfma_f32_16x16x32_bf16 v[116:119], v[128:131], v[186:189], v[116:119]
	v_mfma_f32_16x16x32_bf16 v[112:115], v[136:139], v[186:189], v[112:115]
	v_mfma_f32_16x16x32_bf16 v[108:111], v[128:131], v[194:197], v[108:111]
	v_mfma_f32_16x16x32_bf16 v[104:107], v[136:139], v[194:197], v[104:107]
	v_mfma_f32_16x16x32_bf16 v[92:95], v[128:131], v[210:213], v[92:95]
	v_mfma_f32_16x16x32_bf16 v[84:87], v[136:139], v[210:213], v[84:87]
	v_mfma_f32_16x16x32_bf16 v[124:127], v[132:135], v[164:167], v[124:127]
	v_mfma_f32_16x16x32_bf16 v[120:123], v[140:143], v[164:167], v[120:123]
	v_mfma_f32_16x16x32_bf16 v[116:119], v[132:135], v[190:193], v[116:119]
	v_mfma_f32_16x16x32_bf16 v[112:115], v[140:143], v[190:193], v[112:115]
	v_mfma_f32_16x16x32_bf16 v[108:111], v[132:135], v[198:201], v[108:111]
	v_mfma_f32_16x16x32_bf16 v[104:107], v[140:143], v[198:201], v[104:107]
	v_mfma_f32_16x16x32_bf16 v[92:95], v[132:135], v[218:221], v[92:95]
	v_mfma_f32_16x16x32_bf16 v[84:87], v[140:143], v[218:221], v[84:87]
	v_mfma_f32_16x16x32_bf16 v[88:91], v[144:147], v[160:163], v[88:91]
	v_mfma_f32_16x16x32_bf16 v[24:27], v[152:155], v[160:163], v[24:27]
	v_mfma_f32_16x16x32_bf16 v[100:103], v[144:147], v[186:189], v[100:103]
	v_mfma_f32_16x16x32_bf16 v[36:39], v[152:155], v[186:189], v[36:39]
	v_mfma_f32_16x16x32_bf16 v[96:99], v[144:147], v[194:197], v[96:99]
	v_mfma_f32_16x16x32_bf16 v[52:55], v[152:155], v[194:197], v[52:55]
	v_mfma_f32_16x16x32_bf16 v[80:83], v[144:147], v[210:213], v[80:83]
	v_mfma_f32_16x16x32_bf16 v[64:67], v[152:155], v[210:213], v[64:67]
	v_mfma_f32_16x16x32_bf16 v[88:91], v[148:151], v[164:167], v[88:91]
	v_mfma_f32_16x16x32_bf16 v[24:27], v[156:159], v[164:167], v[24:27]
	v_mfma_f32_16x16x32_bf16 v[100:103], v[148:151], v[190:193], v[100:103]
	v_mfma_f32_16x16x32_bf16 v[36:39], v[156:159], v[190:193], v[36:39]
	v_mfma_f32_16x16x32_bf16 v[96:99], v[148:151], v[198:201], v[96:99]
	v_mfma_f32_16x16x32_bf16 v[52:55], v[156:159], v[198:201], v[52:55]
	v_mfma_f32_16x16x32_bf16 v[80:83], v[148:151], v[218:221], v[80:83]
	v_mfma_f32_16x16x32_bf16 v[64:67], v[156:159], v[218:221], v[64:67]
	s_setprio 0
	s_barrier
	s_add_i32 s85, s83, s67
	v_lshl_add_u64 v[214:215], s[12:13], 0, v[172:173]
	s_mov_b32 m0, s85
	ds_read_b128 v[160:163], v206 offset:16384
	ds_read_b128 v[164:167], v206 offset:17408
	ds_read_b128 v[186:189], v206 offset:18432
	ds_read_b128 v[190:193], v206 offset:19456
	ds_read_b128 v[194:197], v206 offset:20480
	ds_read_b128 v[198:201], v206 offset:21504
	ds_read_b128 v[210:213], v206 offset:22528
	ds_read_b128 v[218:221], v206 offset:23552
	global_load_lds_dwordx4 v[214:215], off
	s_add_i32 m0, s85, 0x2000
	s_add_u32 s92, s12, 0x40000
	v_lshl_add_u64 v[222:223], s[12:13], 0, v[168:169]
	s_addc_u32 s93, s13, 0
	s_add_i32 s85, s94, s67
	global_load_lds_dwordx4 v[222:223], off
	v_lshl_add_u64 v[224:225], s[92:93], 0, v[172:173]
	s_mov_b32 m0, s85
	v_lshl_add_u64 v[226:227], s[14:15], 0, v[170:171]
	global_load_lds_dwordx4 v[224:225], off
	v_lshl_add_u64 v[224:225], s[92:93], 0, v[168:169]
	s_add_i32 m0, s85, 0x2000
	s_nop 0
	global_load_lds_dwordx4 v[224:225], off
	v_lshl_add_u64 v[224:225], s[14:15], 0, v[174:175]
	s_mov_b32 m0, s53
	s_nop 0
	global_load_lds_dwordx4 v[224:225], off
	s_mov_b32 m0, s68
	s_nop 0
	global_load_lds_dwordx4 v[226:227], off
	s_cmp_lg_u32 s84, -2
	s_cbranch_scc1 .Lzacc2b
	v_mov_b32_e32 v0, 0
	v_mov_b32_e32 v1, 0
	v_mov_b32_e32 v2, 0
	v_mov_b32_e32 v3, 0
	v_mov_b32_e32 v4, 0
	v_mov_b32_e32 v5, 0
	v_mov_b32_e32 v6, 0
	v_mov_b32_e32 v7, 0
	v_mov_b32_e32 v8, 0
	v_mov_b32_e32 v9, 0
	v_mov_b32_e32 v10, 0
	v_mov_b32_e32 v11, 0
	v_mov_b32_e32 v12, 0
	v_mov_b32_e32 v13, 0
	v_mov_b32_e32 v14, 0
	v_mov_b32_e32 v15, 0
	v_mov_b32_e32 v16, 0
	v_mov_b32_e32 v17, 0
	v_mov_b32_e32 v18, 0
	v_mov_b32_e32 v19, 0
	v_mov_b32_e32 v20, 0
	v_mov_b32_e32 v21, 0
	v_mov_b32_e32 v22, 0
	v_mov_b32_e32 v23, 0
	v_mov_b32_e32 v28, 0
	v_mov_b32_e32 v29, 0
	v_mov_b32_e32 v30, 0
	v_mov_b32_e32 v31, 0
	v_mov_b32_e32 v32, 0
	v_mov_b32_e32 v33, 0
	v_mov_b32_e32 v34, 0
	v_mov_b32_e32 v35, 0
	v_mov_b32_e32 v40, 0
	v_mov_b32_e32 v41, 0
	v_mov_b32_e32 v42, 0
	v_mov_b32_e32 v43, 0
	v_mov_b32_e32 v44, 0
	v_mov_b32_e32 v45, 0
	v_mov_b32_e32 v46, 0
	v_mov_b32_e32 v47, 0
	v_mov_b32_e32 v48, 0
	v_mov_b32_e32 v49, 0
	v_mov_b32_e32 v50, 0
	v_mov_b32_e32 v51, 0
	v_mov_b32_e32 v56, 0
	v_mov_b32_e32 v57, 0
	v_mov_b32_e32 v58, 0
	v_mov_b32_e32 v59, 0
	v_mov_b32_e32 v60, 0
	v_mov_b32_e32 v61, 0
	v_mov_b32_e32 v62, 0
	v_mov_b32_e32 v63, 0
	v_mov_b32_e32 v68, 0
	v_mov_b32_e32 v69, 0
	v_mov_b32_e32 v70, 0
	v_mov_b32_e32 v71, 0
	v_mov_b32_e32 v72, 0
	v_mov_b32_e32 v73, 0
	v_mov_b32_e32 v74, 0
	v_mov_b32_e32 v75, 0
	v_mov_b32_e32 v76, 0
	v_mov_b32_e32 v77, 0
	v_mov_b32_e32 v78, 0
	v_mov_b32_e32 v79, 0
.Lzacc2b:
	s_waitcnt vmcnt(8)
	s_waitcnt lgkmcnt(0)
	s_barrier
	s_setprio 1
	s_waitcnt lgkmcnt(0)
	v_mfma_f32_16x16x32_bf16 v[76:79], v[128:131], v[160:163], v[76:79]
	v_mfma_f32_16x16x32_bf16 v[72:75], v[136:139], v[160:163], v[72:75]
	v_mfma_f32_16x16x32_bf16 v[60:63], v[128:131], v[186:189], v[60:63]
	v_mfma_f32_16x16x32_bf16 v[56:59], v[136:139], v[186:189], v[56:59]
	v_mfma_f32_16x16x32_bf16 v[44:47], v[128:131], v[194:197], v[44:47]
	v_mfma_f32_16x16x32_bf16 v[40:43], v[136:139], v[194:197], v[40:43]
	v_mfma_f32_16x16x32_bf16 v[20:23], v[128:131], v[210:213], v[20:23]
	v_mfma_f32_16x16x32_bf16 v[8:11], v[136:139], v[210:213], v[8:11]
	v_mfma_f32_16x16x32_bf16 v[76:79], v[132:135], v[164:167], v[76:79]
	v_mfma_f32_16x16x32_bf16 v[72:75], v[140:143], v[164:167], v[72:75]
	v_mfma_f32_16x16x32_bf16 v[60:63], v[132:135], v[190:193], v[60:63]
	v_mfma_f32_16x16x32_bf16 v[56:59], v[140:143], v[190:193], v[56:59]
	v_mfma_f32_16x16x32_bf16 v[44:47], v[132:135], v[198:201], v[44:47]
	v_mfma_f32_16x16x32_bf16 v[40:43], v[140:143], v[198:201], v[40:43]
	v_mfma_f32_16x16x32_bf16 v[20:23], v[132:135], v[218:221], v[20:23]
	v_mfma_f32_16x16x32_bf16 v[8:11], v[140:143], v[218:221], v[8:11]
	v_mfma_f32_16x16x32_bf16 v[68:71], v[144:147], v[160:163], v[68:71]
	v_mfma_f32_16x16x32_bf16 v[12:15], v[152:155], v[160:163], v[12:15]
	v_mfma_f32_16x16x32_bf16 v[48:51], v[144:147], v[186:189], v[48:51]
	v_mfma_f32_16x16x32_bf16 v[28:31], v[152:155], v[186:189], v[28:31]
	v_mfma_f32_16x16x32_bf16 v[32:35], v[144:147], v[194:197], v[32:35]
	v_mfma_f32_16x16x32_bf16 v[16:19], v[152:155], v[194:197], v[16:19]
	v_mfma_f32_16x16x32_bf16 v[4:7], v[144:147], v[210:213], v[4:7]
	v_mfma_f32_16x16x32_bf16 v[0:3], v[152:155], v[210:213], v[0:3]
	v_mfma_f32_16x16x32_bf16 v[68:71], v[148:151], v[164:167], v[68:71]
	v_mfma_f32_16x16x32_bf16 v[12:15], v[156:159], v[164:167], v[12:15]
	v_mfma_f32_16x16x32_bf16 v[48:51], v[148:151], v[190:193], v[48:51]
	v_mfma_f32_16x16x32_bf16 v[28:31], v[156:159], v[190:193], v[28:31]
	v_mfma_f32_16x16x32_bf16 v[32:35], v[148:151], v[198:201], v[32:35]
	v_mfma_f32_16x16x32_bf16 v[16:19], v[156:159], v[198:201], v[16:19]
	v_mfma_f32_16x16x32_bf16 v[4:7], v[148:151], v[218:221], v[4:7]
	v_mfma_f32_16x16x32_bf16 v[0:3], v[156:159], v[218:221], v[0:3]
	s_setprio 0
	s_barrier
	s_add_i32 s85, 0, 0x18000
	s_add_i32 s89, 0, 0x1c000
	v_add_u32_e32 v140, s85, v203
	v_add_u32_e32 v156, s89, v203
	ds_read_b128 v[128:131], v140
	ds_read_b128 v[132:135], v140 offset:1024
	ds_read_b128 v[136:139], v140 offset:2048
	ds_read_b128 v[140:143], v140 offset:3072
	ds_read_b128 v[144:147], v156
	ds_read_b128 v[148:151], v156 offset:1024
	ds_read_b128 v[152:155], v156 offset:2048
	ds_read_b128 v[156:159], v156 offset:3072
	s_add_u32 s14, s14, 0x40000
	s_addc_u32 s15, s15, 0
	s_mov_b32 m0, s69
	v_lshl_add_u64 v[228:229], s[14:15], 0, v[174:175]
	ds_read_b128 v[160:163], v206 offset:32768
	ds_read_b128 v[164:167], v206 offset:33792
	ds_read_b128 v[186:189], v206 offset:34816
	ds_read_b128 v[190:193], v206 offset:35840
	ds_read_b128 v[194:197], v206 offset:36864
	ds_read_b128 v[198:201], v206 offset:37888
	ds_read_b128 v[210:213], v206 offset:38912
	ds_read_b128 v[218:221], v206 offset:39936
	global_load_lds_dwordx4 v[228:229], off
	v_lshl_add_u64 v[228:229], s[14:15], 0, v[170:171]
	s_mov_b32 m0, s72
	s_nop 0
	global_load_lds_dwordx4 v[228:229], off
	s_waitcnt vmcnt(8)
	s_waitcnt lgkmcnt(0)
	s_barrier
	s_setprio 1
	s_waitcnt lgkmcnt(0)
	v_mfma_f32_16x16x32_bf16 v[124:127], v[128:131], v[160:163], v[124:127]
	v_mfma_f32_16x16x32_bf16 v[120:123], v[136:139], v[160:163], v[120:123]
	v_mfma_f32_16x16x32_bf16 v[116:119], v[128:131], v[186:189], v[116:119]
	v_mfma_f32_16x16x32_bf16 v[112:115], v[136:139], v[186:189], v[112:115]
	v_mfma_f32_16x16x32_bf16 v[108:111], v[128:131], v[194:197], v[108:111]
	v_mfma_f32_16x16x32_bf16 v[104:107], v[136:139], v[194:197], v[104:107]
	v_mfma_f32_16x16x32_bf16 v[92:95], v[128:131], v[210:213], v[92:95]
	v_mfma_f32_16x16x32_bf16 v[84:87], v[136:139], v[210:213], v[84:87]
	v_mfma_f32_16x16x32_bf16 v[124:127], v[132:135], v[164:167], v[124:127]
	v_mfma_f32_16x16x32_bf16 v[120:123], v[140:143], v[164:167], v[120:123]
	v_mfma_f32_16x16x32_bf16 v[116:119], v[132:135], v[190:193], v[116:119]
	v_mfma_f32_16x16x32_bf16 v[112:115], v[140:143], v[190:193], v[112:115]
	v_mfma_f32_16x16x32_bf16 v[108:111], v[132:135], v[198:201], v[108:111]
	v_mfma_f32_16x16x32_bf16 v[104:107], v[140:143], v[198:201], v[104:107]
	v_mfma_f32_16x16x32_bf16 v[92:95], v[132:135], v[218:221], v[92:95]
	v_mfma_f32_16x16x32_bf16 v[84:87], v[140:143], v[218:221], v[84:87]
	v_mfma_f32_16x16x32_bf16 v[88:91], v[144:147], v[160:163], v[88:91]
	v_mfma_f32_16x16x32_bf16 v[24:27], v[152:155], v[160:163], v[24:27]
	v_mfma_f32_16x16x32_bf16 v[100:103], v[144:147], v[186:189], v[100:103]
	v_mfma_f32_16x16x32_bf16 v[36:39], v[152:155], v[186:189], v[36:39]
	v_mfma_f32_16x16x32_bf16 v[96:99], v[144:147], v[194:197], v[96:99]
	v_mfma_f32_16x16x32_bf16 v[52:55], v[152:155], v[194:197], v[52:55]
	v_mfma_f32_16x16x32_bf16 v[80:83], v[144:147], v[210:213], v[80:83]
	v_mfma_f32_16x16x32_bf16 v[64:67], v[152:155], v[210:213], v[64:67]
	v_mfma_f32_16x16x32_bf16 v[88:91], v[148:151], v[164:167], v[88:91]
	v_mfma_f32_16x16x32_bf16 v[24:27], v[156:159], v[164:167], v[24:27]
	v_mfma_f32_16x16x32_bf16 v[100:103], v[148:151], v[190:193], v[100:103]
	v_mfma_f32_16x16x32_bf16 v[36:39], v[156:159], v[190:193], v[36:39]
	v_mfma_f32_16x16x32_bf16 v[96:99], v[148:151], v[198:201], v[96:99]
	v_mfma_f32_16x16x32_bf16 v[52:55], v[156:159], v[198:201], v[52:55]
	v_mfma_f32_16x16x32_bf16 v[80:83], v[148:151], v[218:221], v[80:83]
	v_mfma_f32_16x16x32_bf16 v[64:67], v[156:159], v[218:221], v[64:67]
	s_setprio 0
	s_barrier
	s_add_i32 s14, s85, s67
	v_lshl_add_u64 v[214:215], v[214:215], 0, s[30:31]
	s_mov_b32 m0, s14
	ds_read_b128 v[160:163], v206 offset:49152
	ds_read_b128 v[164:167], v206 offset:50176
	ds_read_b128 v[186:189], v206 offset:51200
	ds_read_b128 v[190:193], v206 offset:52224
	ds_read_b128 v[194:197], v206 offset:53248
	ds_read_b128 v[198:201], v206 offset:54272
	ds_read_b128 v[210:213], v206 offset:55296
	ds_read_b128 v[218:221], v206 offset:56320
	global_load_lds_dwordx4 v[214:215], off
	s_add_i32 m0, s14, 0x2000
	s_add_u32 s12, s12, 0x40080
	v_lshl_add_u64 v[214:215], v[222:223], 0, s[30:31]
	s_addc_u32 s13, s13, 0
	s_add_i32 s14, s89, s67
	global_load_lds_dwordx4 v[214:215], off
	v_lshl_add_u64 v[214:215], s[12:13], 0, v[172:173]
	s_mov_b32 m0, s14
	s_nop 0
	global_load_lds_dwordx4 v[214:215], off
	v_lshl_add_u64 v[214:215], s[12:13], 0, v[168:169]
	s_add_i32 m0, s14, 0x2000
	s_nop 0
	global_load_lds_dwordx4 v[214:215], off
	v_lshl_add_u64 v[214:215], v[224:225], 0, s[30:31]
	s_mov_b32 m0, s77
	s_nop 0
	global_load_lds_dwordx4 v[214:215], off
	v_lshl_add_u64 v[214:215], v[226:227], 0, s[30:31]
	s_mov_b32 m0, s78
	s_nop 0
	global_load_lds_dwordx4 v[214:215], off
	s_waitcnt vmcnt(8)
	s_waitcnt lgkmcnt(0)
	s_barrier
	s_setprio 1
	s_waitcnt lgkmcnt(0)
	v_mfma_f32_16x16x32_bf16 v[76:79], v[128:131], v[160:163], v[76:79]
	v_mfma_f32_16x16x32_bf16 v[72:75], v[136:139], v[160:163], v[72:75]
	v_mfma_f32_16x16x32_bf16 v[60:63], v[128:131], v[186:189], v[60:63]
	v_mfma_f32_16x16x32_bf16 v[56:59], v[136:139], v[186:189], v[56:59]
	v_mfma_f32_16x16x32_bf16 v[44:47], v[128:131], v[194:197], v[44:47]
	v_mfma_f32_16x16x32_bf16 v[40:43], v[136:139], v[194:197], v[40:43]
	v_mfma_f32_16x16x32_bf16 v[20:23], v[128:131], v[210:213], v[20:23]
	v_mfma_f32_16x16x32_bf16 v[8:11], v[136:139], v[210:213], v[8:11]
	v_mfma_f32_16x16x32_bf16 v[76:79], v[132:135], v[164:167], v[76:79]
	v_mfma_f32_16x16x32_bf16 v[72:75], v[140:143], v[164:167], v[72:75]
	v_mfma_f32_16x16x32_bf16 v[60:63], v[132:135], v[190:193], v[60:63]
	v_mfma_f32_16x16x32_bf16 v[56:59], v[140:143], v[190:193], v[56:59]
	v_mfma_f32_16x16x32_bf16 v[44:47], v[132:135], v[198:201], v[44:47]
	v_mfma_f32_16x16x32_bf16 v[40:43], v[140:143], v[198:201], v[40:43]
	v_mfma_f32_16x16x32_bf16 v[20:23], v[132:135], v[218:221], v[20:23]
	v_mfma_f32_16x16x32_bf16 v[8:11], v[140:143], v[218:221], v[8:11]
	v_mfma_f32_16x16x32_bf16 v[68:71], v[144:147], v[160:163], v[68:71]
	v_mfma_f32_16x16x32_bf16 v[12:15], v[152:155], v[160:163], v[12:15]
	v_mfma_f32_16x16x32_bf16 v[48:51], v[144:147], v[186:189], v[48:51]
	v_mfma_f32_16x16x32_bf16 v[28:31], v[152:155], v[186:189], v[28:31]
	v_mfma_f32_16x16x32_bf16 v[32:35], v[144:147], v[194:197], v[32:35]
	v_mfma_f32_16x16x32_bf16 v[16:19], v[152:155], v[194:197], v[16:19]
	v_mfma_f32_16x16x32_bf16 v[4:7], v[144:147], v[210:213], v[4:7]
	v_mfma_f32_16x16x32_bf16 v[0:3], v[152:155], v[210:213], v[0:3]
	v_mfma_f32_16x16x32_bf16 v[68:71], v[148:151], v[164:167], v[68:71]
	v_mfma_f32_16x16x32_bf16 v[12:15], v[156:159], v[164:167], v[12:15]
	v_mfma_f32_16x16x32_bf16 v[48:51], v[148:151], v[190:193], v[48:51]
	v_mfma_f32_16x16x32_bf16 v[28:31], v[156:159], v[190:193], v[28:31]
	v_mfma_f32_16x16x32_bf16 v[32:35], v[148:151], v[198:201], v[32:35]
	v_mfma_f32_16x16x32_bf16 v[16:19], v[156:159], v[198:201], v[16:19]
	v_mfma_f32_16x16x32_bf16 v[4:7], v[148:151], v[218:221], v[4:7]
	v_mfma_f32_16x16x32_bf16 v[0:3], v[156:159], v[218:221], v[0:3]
	s_setprio 0
	s_barrier
	s_add_i32 s84, s84, 2
	s_add_u32 s10, s10, 0x100
	s_addc_u32 s11, s11, 0
	s_add_u32 s57, s57, 0x100
	s_addc_u32 s59, s59, 0
	s_cmp_gt_u32 s84, 13
	s_cbranch_scc0 .LBB0_381
	s_and_b64 vcc, exec, s[34:35]
	s_cbranch_vccz .LBB0_384
	s_barrier

.Lzacc3a:
	s_waitcnt vmcnt(8)
	s_waitcnt lgkmcnt(0)
	s_barrier
	s_setprio 1
	s_waitcnt lgkmcnt(0)
	v_mfma_f32_16x16x32_bf16 v[132:135], v[112:115], v[160:163], v[132:135]
	v_mfma_f32_16x16x32_bf16 v[128:131], v[136:139], v[160:163], v[128:131]
	v_mfma_f32_16x16x32_bf16 v[108:111], v[112:115], v[168:171], v[108:111]
	v_mfma_f32_16x16x32_bf16 v[104:107], v[136:139], v[168:171], v[104:107]
	v_mfma_f32_16x16x32_bf16 v[92:95], v[112:115], v[176:179], v[92:95]
	v_mfma_f32_16x16x32_bf16 v[88:91], v[136:139], v[176:179], v[88:91]
	v_mfma_f32_16x16x32_bf16 v[76:79], v[112:115], v[200:203], v[76:79]
	v_mfma_f32_16x16x32_bf16 v[72:75], v[136:139], v[200:203], v[72:75]
	v_mfma_f32_16x16x32_bf16 v[132:135], v[124:127], v[164:167], v[132:135]
	v_mfma_f32_16x16x32_bf16 v[128:131], v[140:143], v[164:167], v[128:131]
	v_mfma_f32_16x16x32_bf16 v[108:111], v[124:127], v[172:175], v[108:111]
	v_mfma_f32_16x16x32_bf16 v[104:107], v[140:143], v[172:175], v[104:107]
	v_mfma_f32_16x16x32_bf16 v[92:95], v[124:127], v[180:183], v[92:95]
	v_mfma_f32_16x16x32_bf16 v[88:91], v[140:143], v[180:183], v[88:91]
	v_mfma_f32_16x16x32_bf16 v[76:79], v[124:127], v[204:207], v[76:79]
	v_mfma_f32_16x16x32_bf16 v[72:75], v[140:143], v[204:207], v[72:75]
	v_mfma_f32_16x16x32_bf16 v[120:123], v[144:147], v[160:163], v[120:123]
	v_mfma_f32_16x16x32_bf16 v[116:119], v[152:155], v[160:163], v[116:119]
	v_mfma_f32_16x16x32_bf16 v[100:103], v[144:147], v[168:171], v[100:103]
	v_mfma_f32_16x16x32_bf16 v[96:99], v[152:155], v[168:171], v[96:99]
	v_mfma_f32_16x16x32_bf16 v[84:87], v[144:147], v[176:179], v[84:87]
	v_mfma_f32_16x16x32_bf16 v[80:83], v[152:155], v[176:179], v[80:83]
	v_mfma_f32_16x16x32_bf16 v[68:71], v[144:147], v[200:203], v[68:71]
	v_mfma_f32_16x16x32_bf16 v[64:67], v[152:155], v[200:203], v[64:67]
	v_mfma_f32_16x16x32_bf16 v[120:123], v[148:151], v[164:167], v[120:123]
	v_mfma_f32_16x16x32_bf16 v[116:119], v[156:159], v[164:167], v[116:119]
	v_mfma_f32_16x16x32_bf16 v[100:103], v[148:151], v[172:175], v[100:103]
	v_mfma_f32_16x16x32_bf16 v[96:99], v[156:159], v[172:175], v[96:99]
	v_mfma_f32_16x16x32_bf16 v[84:87], v[148:151], v[180:183], v[84:87]
	v_mfma_f32_16x16x32_bf16 v[80:83], v[156:159], v[180:183], v[80:83]
	v_mfma_f32_16x16x32_bf16 v[68:71], v[148:151], v[204:207], v[68:71]
	v_mfma_f32_16x16x32_bf16 v[64:67], v[156:159], v[204:207], v[64:67]
	s_setprio 0
	s_barrier
	s_add_i32 s58, s78, s68
	v_lshl_add_u64 v[208:209], s[62:63], 0, v[186:187]
	s_mov_b32 m0, s58
	ds_read_b128 v[160:163], v225 offset:16384
	ds_read_b128 v[164:167], v225 offset:17408
	ds_read_b128 v[168:171], v225 offset:18432
	ds_read_b128 v[172:175], v225 offset:19456
	ds_read_b128 v[176:179], v225 offset:20480
	ds_read_b128 v[180:183], v225 offset:21504
	ds_read_b128 v[200:203], v225 offset:22528
	ds_read_b128 v[204:207], v225 offset:23552
	global_load_lds_dwordx4 v[208:209], off
	s_add_i32 m0, s58, 0x2000
	s_add_u32 s58, s62, 0xb0000
	v_lshl_add_u64 v[210:211], s[62:63], 0, v[190:191]
	s_addc_u32 s59, s63, 0
	s_add_i32 s83, s79, s68
	global_load_lds_dwordx4 v[210:211], off
	v_lshl_add_u64 v[212:213], s[58:59], 0, v[186:187]
	s_mov_b32 m0, s83
	v_lshl_add_u64 v[214:215], s[64:65], 0, v[188:189]
	global_load_lds_dwordx4 v[212:213], off
	v_lshl_add_u64 v[212:213], s[58:59], 0, v[190:191]
	s_add_i32 m0, s83, 0x2000
	s_nop 0
	global_load_lds_dwordx4 v[212:213], off
	v_lshl_add_u64 v[212:213], s[64:65], 0, v[184:185]
	s_mov_b32 m0, s69
	s_nop 0
	global_load_lds_dwordx4 v[212:213], off
	s_mov_b32 m0, s72
	s_nop 0
	global_load_lds_dwordx4 v[214:215], off
	s_cmp_lg_u32 s55, -2
	s_cbranch_scc1 .Lzacc3b
	v_mov_b32_e32 v0, 0
	v_mov_b32_e32 v1, 0
	v_mov_b32_e32 v2, 0
	v_mov_b32_e32 v3, 0
	v_mov_b32_e32 v4, 0
	v_mov_b32_e32 v5, 0
	v_mov_b32_e32 v6, 0
	v_mov_b32_e32 v7, 0
	v_mov_b32_e32 v8, 0
	v_mov_b32_e32 v9, 0
	v_mov_b32_e32 v10, 0
	v_mov_b32_e32 v11, 0
	v_mov_b32_e32 v12, 0
	v_mov_b32_e32 v13, 0
	v_mov_b32_e32 v14, 0
	v_mov_b32_e32 v15, 0
	v_mov_b32_e32 v16, 0
	v_mov_b32_e32 v17, 0
	v_mov_b32_e32 v18, 0
	v_mov_b32_e32 v19, 0
	v_mov_b32_e32 v20, 0
	v_mov_b32_e32 v21, 0
	v_mov_b32_e32 v22, 0
	v_mov_b32_e32 v23, 0
	v_mov_b32_e32 v24, 0
	v_mov_b32_e32 v25, 0
	v_mov_b32_e32 v26, 0
	v_mov_b32_e32 v27, 0
	v_mov_b32_e32 v28, 0
	v_mov_b32_e32 v29, 0
	v_mov_b32_e32 v30, 0
	v_mov_b32_e32 v31, 0
	v_mov_b32_e32 v32, 0
	v_mov_b32_e32 v33, 0
	v_mov_b32_e32 v34, 0
	v_mov_b32_e32 v35, 0
	v_mov_b32_e32 v36, 0
	v_mov_b32_e32 v37, 0
	v_mov_b32_e32 v38, 0
	v_mov_b32_e32 v39, 0
	v_mov_b32_e32 v40, 0
	v_mov_b32_e32 v41, 0
	v_mov_b32_e32 v42, 0
	v_mov_b32_e32 v43, 0
	v_mov_b32_e32 v44, 0
	v_mov_b32_e32 v45, 0
	v_mov_b32_e32 v46, 0
	v_mov_b32_e32 v47, 0
	v_mov_b32_e32 v48, 0
	v_mov_b32_e32 v49, 0
	v_mov_b32_e32 v50, 0
	v_mov_b32_e32 v51, 0
	v_mov_b32_e32 v52, 0
	v_mov_b32_e32 v53, 0
	v_mov_b32_e32 v54, 0
	v_mov_b32_e32 v55, 0
	v_mov_b32_e32 v56, 0
	v_mov_b32_e32 v57, 0
	v_mov_b32_e32 v58, 0
	v_mov_b32_e32 v59, 0
	v_mov_b32_e32 v60, 0
	v_mov_b32_e32 v61, 0
	v_mov_b32_e32 v62, 0
	v_mov_b32_e32 v63, 0
.Lzacc3b:
	s_waitcnt vmcnt(8)
	s_waitcnt lgkmcnt(0)
	s_barrier
	s_setprio 1
	s_waitcnt lgkmcnt(0)
	v_mfma_f32_16x16x32_bf16 v[60:63], v[112:115], v[160:163], v[60:63]
	v_mfma_f32_16x16x32_bf16 v[56:59], v[136:139], v[160:163], v[56:59]
	v_mfma_f32_16x16x32_bf16 v[44:47], v[112:115], v[168:171], v[44:47]
	v_mfma_f32_16x16x32_bf16 v[40:43], v[136:139], v[168:171], v[40:43]
	v_mfma_f32_16x16x32_bf16 v[28:31], v[112:115], v[176:179], v[28:31]
	v_mfma_f32_16x16x32_bf16 v[24:27], v[136:139], v[176:179], v[24:27]
	v_mfma_f32_16x16x32_bf16 v[12:15], v[112:115], v[200:203], v[12:15]
	v_mfma_f32_16x16x32_bf16 v[8:11], v[136:139], v[200:203], v[8:11]
	v_mfma_f32_16x16x32_bf16 v[60:63], v[124:127], v[164:167], v[60:63]
	v_mfma_f32_16x16x32_bf16 v[56:59], v[140:143], v[164:167], v[56:59]
	v_mfma_f32_16x16x32_bf16 v[44:47], v[124:127], v[172:175], v[44:47]
	v_mfma_f32_16x16x32_bf16 v[40:43], v[140:143], v[172:175], v[40:43]
	v_mfma_f32_16x16x32_bf16 v[28:31], v[124:127], v[180:183], v[28:31]
	v_mfma_f32_16x16x32_bf16 v[24:27], v[140:143], v[180:183], v[24:27]
	v_mfma_f32_16x16x32_bf16 v[12:15], v[124:127], v[204:207], v[12:15]
	v_mfma_f32_16x16x32_bf16 v[8:11], v[140:143], v[204:207], v[8:11]
	v_mfma_f32_16x16x32_bf16 v[52:55], v[144:147], v[160:163], v[52:55]
	v_mfma_f32_16x16x32_bf16 v[48:51], v[152:155], v[160:163], v[48:51]
	v_mfma_f32_16x16x32_bf16 v[36:39], v[144:147], v[168:171], v[36:39]
	v_mfma_f32_16x16x32_bf16 v[32:35], v[152:155], v[168:171], v[32:35]
	v_mfma_f32_16x16x32_bf16 v[20:23], v[144:147], v[176:179], v[20:23]
	v_mfma_f32_16x16x32_bf16 v[16:19], v[152:155], v[176:179], v[16:19]
	v_mfma_f32_16x16x32_bf16 v[4:7], v[144:147], v[200:203], v[4:7]
	v_mfma_f32_16x16x32_bf16 v[0:3], v[152:155], v[200:203], v[0:3]
	v_mfma_f32_16x16x32_bf16 v[52:55], v[148:151], v[164:167], v[52:55]
	v_mfma_f32_16x16x32_bf16 v[48:51], v[156:159], v[164:167], v[48:51]
	v_mfma_f32_16x16x32_bf16 v[36:39], v[148:151], v[172:175], v[36:39]
	v_mfma_f32_16x16x32_bf16 v[32:35], v[156:159], v[172:175], v[32:35]
	v_mfma_f32_16x16x32_bf16 v[20:23], v[148:151], v[180:183], v[20:23]
	v_mfma_f32_16x16x32_bf16 v[16:19], v[156:159], v[180:183], v[16:19]
	v_mfma_f32_16x16x32_bf16 v[4:7], v[148:151], v[204:207], v[4:7]
	v_mfma_f32_16x16x32_bf16 v[0:3], v[156:159], v[204:207], v[0:3]
	s_setprio 0
	s_barrier
	s_add_i32 s83, 0, 0x18000
	s_add_i32 s84, 0, 0x1c000
	v_add_u32_e32 v140, s83, v220
	v_add_u32_e32 v156, s84, v220
	ds_read_b128 v[112:115], v140
	ds_read_b128 v[124:127], v140 offset:1024
	ds_read_b128 v[136:139], v140 offset:2048
	ds_read_b128 v[140:143], v140 offset:3072
	ds_read_b128 v[144:147], v156
	ds_read_b128 v[148:151], v156 offset:1024
	ds_read_b128 v[152:155], v156 offset:2048
	ds_read_b128 v[156:159], v156 offset:3072
	s_add_u32 s58, s64, 0xb0000
	s_addc_u32 s59, s65, 0
	s_mov_b32 m0, s73
	v_lshl_add_u64 v[228:229], s[58:59], 0, v[184:185]
	ds_read_b128 v[160:163], v225 offset:32768
	ds_read_b128 v[164:167], v225 offset:33792
	ds_read_b128 v[168:171], v225 offset:34816
	ds_read_b128 v[172:175], v225 offset:35840
	ds_read_b128 v[176:179], v225 offset:36864
	ds_read_b128 v[180:183], v225 offset:37888
	ds_read_b128 v[200:203], v225 offset:38912
	ds_read_b128 v[204:207], v225 offset:39936
	global_load_lds_dwordx4 v[228:229], off
	v_lshl_add_u64 v[228:229], s[58:59], 0, v[188:189]
	s_mov_b32 m0, s74
	s_nop 0
	global_load_lds_dwordx4 v[228:229], off
	s_waitcnt vmcnt(8)
	s_waitcnt lgkmcnt(0)
	s_barrier
	s_setprio 1
	s_waitcnt lgkmcnt(0)
	v_mfma_f32_16x16x32_bf16 v[132:135], v[112:115], v[160:163], v[132:135]
	v_mfma_f32_16x16x32_bf16 v[128:131], v[136:139], v[160:163], v[128:131]
	v_mfma_f32_16x16x32_bf16 v[108:111], v[112:115], v[168:171], v[108:111]
	v_mfma_f32_16x16x32_bf16 v[104:107], v[136:139], v[168:171], v[104:107]
	v_mfma_f32_16x16x32_bf16 v[92:95], v[112:115], v[176:179], v[92:95]
	v_mfma_f32_16x16x32_bf16 v[88:91], v[136:139], v[176:179], v[88:91]
	v_mfma_f32_16x16x32_bf16 v[76:79], v[112:115], v[200:203], v[76:79]
	v_mfma_f32_16x16x32_bf16 v[72:75], v[136:139], v[200:203], v[72:75]
	v_mfma_f32_16x16x32_bf16 v[132:135], v[124:127], v[164:167], v[132:135]
	v_mfma_f32_16x16x32_bf16 v[128:131], v[140:143], v[164:167], v[128:131]
	v_mfma_f32_16x16x32_bf16 v[108:111], v[124:127], v[172:175], v[108:111]
	v_mfma_f32_16x16x32_bf16 v[104:107], v[140:143], v[172:175], v[104:107]
	v_mfma_f32_16x16x32_bf16 v[92:95], v[124:127], v[180:183], v[92:95]
	v_mfma_f32_16x16x32_bf16 v[88:91], v[140:143], v[180:183], v[88:91]
	v_mfma_f32_16x16x32_bf16 v[76:79], v[124:127], v[204:207], v[76:79]
	v_mfma_f32_16x16x32_bf16 v[72:75], v[140:143], v[204:207], v[72:75]
	v_mfma_f32_16x16x32_bf16 v[120:123], v[144:147], v[160:163], v[120:123]
	v_mfma_f32_16x16x32_bf16 v[116:119], v[152:155], v[160:163], v[116:119]
	v_mfma_f32_16x16x32_bf16 v[100:103], v[144:147], v[168:171], v[100:103]
	v_mfma_f32_16x16x32_bf16 v[96:99], v[152:155], v[168:171], v[96:99]
	v_mfma_f32_16x16x32_bf16 v[84:87], v[144:147], v[176:179], v[84:87]
	v_mfma_f32_16x16x32_bf16 v[80:83], v[152:155], v[176:179], v[80:83]
	v_mfma_f32_16x16x32_bf16 v[68:71], v[144:147], v[200:203], v[68:71]
	v_mfma_f32_16x16x32_bf16 v[64:67], v[152:155], v[200:203], v[64:67]
	v_mfma_f32_16x16x32_bf16 v[120:123], v[148:151], v[164:167], v[120:123]
	v_mfma_f32_16x16x32_bf16 v[116:119], v[156:159], v[164:167], v[116:119]
	v_mfma_f32_16x16x32_bf16 v[100:103], v[148:151], v[172:175], v[100:103]
	v_mfma_f32_16x16x32_bf16 v[96:99], v[156:159], v[172:175], v[96:99]
	v_mfma_f32_16x16x32_bf16 v[84:87], v[148:151], v[180:183], v[84:87]
	v_mfma_f32_16x16x32_bf16 v[80:83], v[156:159], v[180:183], v[80:83]
	v_mfma_f32_16x16x32_bf16 v[68:71], v[148:151], v[204:207], v[68:71]
	v_mfma_f32_16x16x32_bf16 v[64:67], v[156:159], v[204:207], v[64:67]
	s_setprio 0
	s_barrier
	s_add_i32 s58, s83, s68
	v_lshl_add_u64 v[208:209], v[208:209], 0, s[26:27]
	s_mov_b32 m0, s58
	ds_read_b128 v[160:163], v225 offset:49152
	ds_read_b128 v[164:167], v225 offset:50176
	ds_read_b128 v[168:171], v225 offset:51200
	ds_read_b128 v[172:175], v225 offset:52224
	ds_read_b128 v[176:179], v225 offset:53248
	ds_read_b128 v[180:183], v225 offset:54272
	ds_read_b128 v[200:203], v225 offset:55296
	ds_read_b128 v[204:207], v225 offset:56320
	global_load_lds_dwordx4 v[208:209], off
	s_add_i32 m0, s58, 0x2000
	s_add_u32 s58, s62, 0xb0080
	v_lshl_add_u64 v[208:209], v[210:211], 0, s[26:27]
	s_addc_u32 s59, s63, 0
	s_add_i32 s62, s84, s68
	global_load_lds_dwordx4 v[208:209], off
	v_lshl_add_u64 v[208:209], s[58:59], 0, v[186:187]
	s_mov_b32 m0, s62
	s_nop 0
	global_load_lds_dwordx4 v[208:209], off
	v_lshl_add_u64 v[208:209], s[58:59], 0, v[190:191]
	s_add_i32 m0, s62, 0x2000
	s_nop 0
	global_load_lds_dwordx4 v[208:209], off
	v_lshl_add_u64 v[208:209], v[212:213], 0, s[26:27]
	s_mov_b32 m0, s51
	s_nop 0
	global_load_lds_dwordx4 v[208:209], off
	v_lshl_add_u64 v[208:209], v[214:215], 0, s[26:27]
	s_mov_b32 m0, s76
	s_nop 0
	global_load_lds_dwordx4 v[208:209], off
	s_waitcnt vmcnt(8)
	s_waitcnt lgkmcnt(0)
	s_barrier
	s_setprio 1
	s_waitcnt lgkmcnt(0)
	v_mfma_f32_16x16x32_bf16 v[60:63], v[112:115], v[160:163], v[60:63]
	v_mfma_f32_16x16x32_bf16 v[56:59], v[136:139], v[160:163], v[56:59]
	v_mfma_f32_16x16x32_bf16 v[44:47], v[112:115], v[168:171], v[44:47]
	v_mfma_f32_16x16x32_bf16 v[40:43], v[136:139], v[168:171], v[40:43]
	v_mfma_f32_16x16x32_bf16 v[28:31], v[112:115], v[176:179], v[28:31]
	v_mfma_f32_16x16x32_bf16 v[24:27], v[136:139], v[176:179], v[24:27]
	v_mfma_f32_16x16x32_bf16 v[12:15], v[112:115], v[200:203], v[12:15]
	v_mfma_f32_16x16x32_bf16 v[8:11], v[136:139], v[200:203], v[8:11]
	v_mfma_f32_16x16x32_bf16 v[60:63], v[124:127], v[164:167], v[60:63]
	v_mfma_f32_16x16x32_bf16 v[56:59], v[140:143], v[164:167], v[56:59]
	v_mfma_f32_16x16x32_bf16 v[44:47], v[124:127], v[172:175], v[44:47]
	v_mfma_f32_16x16x32_bf16 v[40:43], v[140:143], v[172:175], v[40:43]
	v_mfma_f32_16x16x32_bf16 v[28:31], v[124:127], v[180:183], v[28:31]
	v_mfma_f32_16x16x32_bf16 v[24:27], v[140:143], v[180:183], v[24:27]
	v_mfma_f32_16x16x32_bf16 v[12:15], v[124:127], v[204:207], v[12:15]
	v_mfma_f32_16x16x32_bf16 v[8:11], v[140:143], v[204:207], v[8:11]
	v_mfma_f32_16x16x32_bf16 v[52:55], v[144:147], v[160:163], v[52:55]
	v_mfma_f32_16x16x32_bf16 v[48:51], v[152:155], v[160:163], v[48:51]
	v_mfma_f32_16x16x32_bf16 v[36:39], v[144:147], v[168:171], v[36:39]
	v_mfma_f32_16x16x32_bf16 v[32:35], v[152:155], v[168:171], v[32:35]
	v_mfma_f32_16x16x32_bf16 v[20:23], v[144:147], v[176:179], v[20:23]
	v_mfma_f32_16x16x32_bf16 v[16:19], v[152:155], v[176:179], v[16:19]
	v_mfma_f32_16x16x32_bf16 v[4:7], v[144:147], v[200:203], v[4:7]
	v_mfma_f32_16x16x32_bf16 v[0:3], v[152:155], v[200:203], v[0:3]
	v_mfma_f32_16x16x32_bf16 v[52:55], v[148:151], v[164:167], v[52:55]
	v_mfma_f32_16x16x32_bf16 v[48:51], v[156:159], v[164:167], v[48:51]
	v_mfma_f32_16x16x32_bf16 v[36:39], v[148:151], v[172:175], v[36:39]
	v_mfma_f32_16x16x32_bf16 v[32:35], v[156:159], v[172:175], v[32:35]
	v_mfma_f32_16x16x32_bf16 v[20:23], v[148:151], v[180:183], v[20:23]
	v_mfma_f32_16x16x32_bf16 v[16:19], v[156:159], v[180:183], v[16:19]
	v_mfma_f32_16x16x32_bf16 v[4:7], v[148:151], v[204:207], v[4:7]
	v_mfma_f32_16x16x32_bf16 v[0:3], v[156:159], v[204:207], v[0:3]
	s_setprio 0
	s_barrier
	s_add_i32 s55, s55, 2
	s_add_u32 s15, s15, 0x100
	s_addc_u32 s54, s54, 0
	s_cmp_gt_u32 s55, 41
	s_mov_b64 s[58:59], s[60:61]
	s_cbranch_scc0 .LBB0_541
	s_and_b64 vcc, exec, s[28:29]
	s_cbranch_vccz .LBB0_544
	s_barrier

.Lzacc4a:
	s_waitcnt vmcnt(8)
	s_waitcnt lgkmcnt(0)
	s_barrier
	s_setprio 1
	s_waitcnt lgkmcnt(0)
	v_mfma_f32_16x16x32_bf16 v[124:127], v[160:163], v[192:195], v[124:127]
	v_mfma_f32_16x16x32_bf16 v[120:123], v[168:171], v[192:195], v[120:123]
	v_mfma_f32_16x16x32_bf16 v[116:119], v[160:163], v[200:203], v[116:119]
	v_mfma_f32_16x16x32_bf16 v[108:111], v[168:171], v[200:203], v[108:111]
	v_mfma_f32_16x16x32_bf16 v[100:103], v[160:163], v[208:211], v[100:103]
	v_mfma_f32_16x16x32_bf16 v[92:95], v[168:171], v[208:211], v[92:95]
	v_mfma_f32_16x16x32_bf16 v[84:87], v[160:163], v[218:221], v[84:87]
	v_mfma_f32_16x16x32_bf16 v[76:79], v[168:171], v[218:221], v[76:79]
	v_mfma_f32_16x16x32_bf16 v[124:127], v[164:167], v[196:199], v[124:127]
	v_mfma_f32_16x16x32_bf16 v[120:123], v[172:175], v[196:199], v[120:123]
	v_mfma_f32_16x16x32_bf16 v[116:119], v[164:167], v[204:207], v[116:119]
	v_mfma_f32_16x16x32_bf16 v[108:111], v[172:175], v[204:207], v[108:111]
	v_mfma_f32_16x16x32_bf16 v[100:103], v[164:167], v[212:215], v[100:103]
	v_mfma_f32_16x16x32_bf16 v[92:95], v[172:175], v[212:215], v[92:95]
	v_mfma_f32_16x16x32_bf16 v[84:87], v[164:167], v[222:225], v[84:87]
	v_mfma_f32_16x16x32_bf16 v[76:79], v[172:175], v[222:225], v[76:79]
	v_mfma_f32_16x16x32_bf16 v[112:115], v[176:179], v[192:195], v[112:115]
	v_mfma_f32_16x16x32_bf16 v[104:107], v[184:187], v[192:195], v[104:107]
	v_mfma_f32_16x16x32_bf16 v[96:99], v[176:179], v[200:203], v[96:99]
	v_mfma_f32_16x16x32_bf16 v[88:91], v[184:187], v[200:203], v[88:91]
	v_mfma_f32_16x16x32_bf16 v[80:83], v[176:179], v[208:211], v[80:83]
	v_mfma_f32_16x16x32_bf16 v[72:75], v[184:187], v[208:211], v[72:75]
	v_mfma_f32_16x16x32_bf16 v[68:71], v[176:179], v[218:221], v[68:71]
	v_mfma_f32_16x16x32_bf16 v[64:67], v[184:187], v[218:221], v[64:67]
	v_mfma_f32_16x16x32_bf16 v[112:115], v[180:183], v[196:199], v[112:115]
	v_mfma_f32_16x16x32_bf16 v[104:107], v[188:191], v[196:199], v[104:107]
	v_mfma_f32_16x16x32_bf16 v[96:99], v[180:183], v[204:207], v[96:99]
	v_mfma_f32_16x16x32_bf16 v[88:91], v[188:191], v[204:207], v[88:91]
	v_mfma_f32_16x16x32_bf16 v[80:83], v[180:183], v[212:215], v[80:83]
	v_mfma_f32_16x16x32_bf16 v[72:75], v[188:191], v[212:215], v[72:75]
	v_mfma_f32_16x16x32_bf16 v[68:71], v[180:183], v[222:225], v[68:71]
	v_mfma_f32_16x16x32_bf16 v[64:67], v[188:191], v[222:225], v[64:67]
	s_setprio 0
	s_barrier
	s_add_i32 s69, s63, s54
	v_lshl_add_u64 v[152:153], s[36:37], 0, v[132:133]
	s_mov_b32 m0, s69
	ds_read_b128 v[192:195], v156 offset:16384
	ds_read_b128 v[196:199], v156 offset:17408
	ds_read_b128 v[200:203], v156 offset:18432
	ds_read_b128 v[204:207], v156 offset:19456
	ds_read_b128 v[208:211], v156 offset:20480
	ds_read_b128 v[212:215], v156 offset:21504
	ds_read_b128 v[218:221], v156 offset:22528
	ds_read_b128 v[222:225], v156 offset:23552
	global_load_lds_dwordx4 v[152:153], off
	s_add_i32 m0, s69, 0x2000
	s_add_u32 s72, s36, 0x40000
	v_lshl_add_u64 v[226:227], s[36:37], 0, v[128:129]
	s_addc_u32 s73, s37, 0
	s_add_i32 s69, s64, s54
	global_load_lds_dwordx4 v[226:227], off
	v_lshl_add_u64 v[228:229], s[72:73], 0, v[132:133]
	s_mov_b32 m0, s69
	v_lshl_add_u64 v[230:231], s[38:39], 0, v[130:131]
	global_load_lds_dwordx4 v[228:229], off
	v_lshl_add_u64 v[228:229], s[72:73], 0, v[128:129]
	s_add_i32 m0, s69, 0x2000
	s_nop 0
	global_load_lds_dwordx4 v[228:229], off
	v_lshl_add_u64 v[228:229], s[38:39], 0, v[134:135]
	s_mov_b32 m0, s8
	s_nop 0
	global_load_lds_dwordx4 v[228:229], off
	s_mov_b32 m0, s55
	s_nop 0
	global_load_lds_dwordx4 v[230:231], off
	s_cmp_lg_u32 s68, -2
	s_cbranch_scc1 .Lzacc4b
	v_mov_b32_e32 v0, 0
	v_mov_b32_e32 v1, 0
	v_mov_b32_e32 v2, 0
	v_mov_b32_e32 v3, 0
	v_mov_b32_e32 v4, 0
	v_mov_b32_e32 v5, 0
	v_mov_b32_e32 v6, 0
	v_mov_b32_e32 v7, 0
	v_mov_b32_e32 v8, 0
	v_mov_b32_e32 v9, 0
	v_mov_b32_e32 v10, 0
	v_mov_b32_e32 v11, 0
	v_mov_b32_e32 v12, 0
	v_mov_b32_e32 v13, 0
	v_mov_b32_e32 v14, 0
	v_mov_b32_e32 v15, 0
	v_mov_b32_e32 v16, 0
	v_mov_b32_e32 v17, 0
	v_mov_b32_e32 v18, 0
	v_mov_b32_e32 v19, 0
	v_mov_b32_e32 v20, 0
	v_mov_b32_e32 v21, 0
	v_mov_b32_e32 v22, 0
	v_mov_b32_e32 v23, 0
	v_mov_b32_e32 v24, 0
	v_mov_b32_e32 v25, 0
	v_mov_b32_e32 v26, 0
	v_mov_b32_e32 v27, 0
	v_mov_b32_e32 v28, 0
	v_mov_b32_e32 v29, 0
	v_mov_b32_e32 v30, 0
	v_mov_b32_e32 v31, 0
	v_mov_b32_e32 v32, 0
	v_mov_b32_e32 v33, 0
	v_mov_b32_e32 v34, 0
	v_mov_b32_e32 v35, 0
	v_mov_b32_e32 v36, 0
	v_mov_b32_e32 v37, 0
	v_mov_b32_e32 v38, 0
	v_mov_b32_e32 v39, 0
	v_mov_b32_e32 v40, 0
	v_mov_b32_e32 v41, 0
	v_mov_b32_e32 v42, 0
	v_mov_b32_e32 v43, 0
	v_mov_b32_e32 v44, 0
	v_mov_b32_e32 v45, 0
	v_mov_b32_e32 v46, 0
	v_mov_b32_e32 v47, 0
	v_mov_b32_e32 v48, 0
	v_mov_b32_e32 v49, 0
	v_mov_b32_e32 v50, 0
	v_mov_b32_e32 v51, 0
	v_mov_b32_e32 v52, 0
	v_mov_b32_e32 v53, 0
	v_mov_b32_e32 v54, 0
	v_mov_b32_e32 v55, 0
	v_mov_b32_e32 v56, 0
	v_mov_b32_e32 v57, 0
	v_mov_b32_e32 v58, 0
	v_mov_b32_e32 v59, 0
	v_mov_b32_e32 v60, 0
	v_mov_b32_e32 v61, 0
	v_mov_b32_e32 v62, 0
	v_mov_b32_e32 v63, 0
.Lzacc4b:
	s_waitcnt vmcnt(8)
	s_waitcnt lgkmcnt(0)
	s_barrier
	s_setprio 1
	s_waitcnt lgkmcnt(0)
	v_mfma_f32_16x16x32_bf16 v[60:63], v[160:163], v[192:195], v[60:63]
	v_mfma_f32_16x16x32_bf16 v[56:59], v[168:171], v[192:195], v[56:59]
	v_mfma_f32_16x16x32_bf16 v[52:55], v[160:163], v[200:203], v[52:55]
	v_mfma_f32_16x16x32_bf16 v[44:47], v[168:171], v[200:203], v[44:47]
	v_mfma_f32_16x16x32_bf16 v[36:39], v[160:163], v[208:211], v[36:39]
	v_mfma_f32_16x16x32_bf16 v[28:31], v[168:171], v[208:211], v[28:31]
	v_mfma_f32_16x16x32_bf16 v[20:23], v[160:163], v[218:221], v[20:23]
	v_mfma_f32_16x16x32_bf16 v[12:15], v[168:171], v[218:221], v[12:15]
	v_mfma_f32_16x16x32_bf16 v[60:63], v[164:167], v[196:199], v[60:63]
	v_mfma_f32_16x16x32_bf16 v[56:59], v[172:175], v[196:199], v[56:59]
	v_mfma_f32_16x16x32_bf16 v[52:55], v[164:167], v[204:207], v[52:55]
	v_mfma_f32_16x16x32_bf16 v[44:47], v[172:175], v[204:207], v[44:47]
	v_mfma_f32_16x16x32_bf16 v[36:39], v[164:167], v[212:215], v[36:39]
	v_mfma_f32_16x16x32_bf16 v[28:31], v[172:175], v[212:215], v[28:31]
	v_mfma_f32_16x16x32_bf16 v[20:23], v[164:167], v[222:225], v[20:23]
	v_mfma_f32_16x16x32_bf16 v[12:15], v[172:175], v[222:225], v[12:15]
	v_mfma_f32_16x16x32_bf16 v[48:51], v[176:179], v[192:195], v[48:51]
	v_mfma_f32_16x16x32_bf16 v[40:43], v[184:187], v[192:195], v[40:43]
	v_mfma_f32_16x16x32_bf16 v[32:35], v[176:179], v[200:203], v[32:35]
	v_mfma_f32_16x16x32_bf16 v[24:27], v[184:187], v[200:203], v[24:27]
	v_mfma_f32_16x16x32_bf16 v[16:19], v[176:179], v[208:211], v[16:19]
	v_mfma_f32_16x16x32_bf16 v[8:11], v[184:187], v[208:211], v[8:11]
	v_mfma_f32_16x16x32_bf16 v[4:7], v[176:179], v[218:221], v[4:7]
	v_mfma_f32_16x16x32_bf16 v[0:3], v[184:187], v[218:221], v[0:3]
	v_mfma_f32_16x16x32_bf16 v[48:51], v[180:183], v[196:199], v[48:51]
	v_mfma_f32_16x16x32_bf16 v[40:43], v[188:191], v[196:199], v[40:43]
	v_mfma_f32_16x16x32_bf16 v[32:35], v[180:183], v[204:207], v[32:35]
	v_mfma_f32_16x16x32_bf16 v[24:27], v[188:191], v[204:207], v[24:27]
	v_mfma_f32_16x16x32_bf16 v[16:19], v[180:183], v[212:215], v[16:19]
	v_mfma_f32_16x16x32_bf16 v[8:11], v[188:191], v[212:215], v[8:11]
	v_mfma_f32_16x16x32_bf16 v[4:7], v[180:183], v[222:225], v[4:7]
	v_mfma_f32_16x16x32_bf16 v[0:3], v[188:191], v[222:225], v[0:3]
	s_setprio 0
	s_barrier
	s_add_i32 s69, 0, 0x18000
	v_add_u32_e32 v136, s69, v151
	s_add_i32 s71, 0, 0x1c000
	ds_read_b128 v[160:163], v136
	ds_read_b128 v[164:167], v136 offset:1024
	ds_read_b128 v[168:171], v136 offset:2048
	ds_read_b128 v[172:175], v136 offset:3072
	v_add_u32_e32 v136, s71, v151
	ds_read_b128 v[176:179], v136
	ds_read_b128 v[180:183], v136 offset:1024
	ds_read_b128 v[184:187], v136 offset:2048
	ds_read_b128 v[188:191], v136 offset:3072
	s_add_u32 s38, s38, 0x40000
	s_addc_u32 s39, s39, 0
	s_mov_b32 m0, s56
	v_lshl_add_u64 v[232:233], s[38:39], 0, v[134:135]
	ds_read_b128 v[192:195], v156 offset:32768
	ds_read_b128 v[196:199], v156 offset:33792
	ds_read_b128 v[200:203], v156 offset:34816
	ds_read_b128 v[204:207], v156 offset:35840
	ds_read_b128 v[208:211], v156 offset:36864
	ds_read_b128 v[212:215], v156 offset:37888
	ds_read_b128 v[218:221], v156 offset:38912
	ds_read_b128 v[222:225], v156 offset:39936
	global_load_lds_dwordx4 v[232:233], off
	v_lshl_add_u64 v[232:233], s[38:39], 0, v[130:131]
	s_mov_b32 m0, s57
	s_nop 0
	global_load_lds_dwordx4 v[232:233], off
	s_waitcnt vmcnt(8)
	s_waitcnt lgkmcnt(0)
	s_barrier
	s_setprio 1
	s_waitcnt lgkmcnt(0)
	v_mfma_f32_16x16x32_bf16 v[124:127], v[160:163], v[192:195], v[124:127]
	v_mfma_f32_16x16x32_bf16 v[120:123], v[168:171], v[192:195], v[120:123]
	v_mfma_f32_16x16x32_bf16 v[116:119], v[160:163], v[200:203], v[116:119]
	v_mfma_f32_16x16x32_bf16 v[108:111], v[168:171], v[200:203], v[108:111]
	v_mfma_f32_16x16x32_bf16 v[100:103], v[160:163], v[208:211], v[100:103]
	v_mfma_f32_16x16x32_bf16 v[92:95], v[168:171], v[208:211], v[92:95]
	v_mfma_f32_16x16x32_bf16 v[84:87], v[160:163], v[218:221], v[84:87]
	v_mfma_f32_16x16x32_bf16 v[76:79], v[168:171], v[218:221], v[76:79]
	v_mfma_f32_16x16x32_bf16 v[124:127], v[164:167], v[196:199], v[124:127]
	v_mfma_f32_16x16x32_bf16 v[120:123], v[172:175], v[196:199], v[120:123]
	v_mfma_f32_16x16x32_bf16 v[116:119], v[164:167], v[204:207], v[116:119]
	v_mfma_f32_16x16x32_bf16 v[108:111], v[172:175], v[204:207], v[108:111]
	v_mfma_f32_16x16x32_bf16 v[100:103], v[164:167], v[212:215], v[100:103]
	v_mfma_f32_16x16x32_bf16 v[92:95], v[172:175], v[212:215], v[92:95]
	v_mfma_f32_16x16x32_bf16 v[84:87], v[164:167], v[222:225], v[84:87]
	v_mfma_f32_16x16x32_bf16 v[76:79], v[172:175], v[222:225], v[76:79]
	v_mfma_f32_16x16x32_bf16 v[112:115], v[176:179], v[192:195], v[112:115]
	v_mfma_f32_16x16x32_bf16 v[104:107], v[184:187], v[192:195], v[104:107]
	v_mfma_f32_16x16x32_bf16 v[96:99], v[176:179], v[200:203], v[96:99]
	v_mfma_f32_16x16x32_bf16 v[88:91], v[184:187], v[200:203], v[88:91]
	v_mfma_f32_16x16x32_bf16 v[80:83], v[176:179], v[208:211], v[80:83]
	v_mfma_f32_16x16x32_bf16 v[72:75], v[184:187], v[208:211], v[72:75]
	v_mfma_f32_16x16x32_bf16 v[68:71], v[176:179], v[218:221], v[68:71]
	v_mfma_f32_16x16x32_bf16 v[64:67], v[184:187], v[218:221], v[64:67]
	v_mfma_f32_16x16x32_bf16 v[112:115], v[180:183], v[196:199], v[112:115]
	v_mfma_f32_16x16x32_bf16 v[104:107], v[188:191], v[196:199], v[104:107]
	v_mfma_f32_16x16x32_bf16 v[96:99], v[180:183], v[204:207], v[96:99]
	v_mfma_f32_16x16x32_bf16 v[88:91], v[188:191], v[204:207], v[88:91]
	v_mfma_f32_16x16x32_bf16 v[80:83], v[180:183], v[212:215], v[80:83]
	v_mfma_f32_16x16x32_bf16 v[72:75], v[188:191], v[212:215], v[72:75]
	v_mfma_f32_16x16x32_bf16 v[68:71], v[180:183], v[222:225], v[68:71]
	v_mfma_f32_16x16x32_bf16 v[64:67], v[188:191], v[222:225], v[64:67]
	s_setprio 0
	s_barrier
	s_add_i32 s38, s69, s54
	v_lshl_add_u64 v[152:153], v[152:153], 0, s[14:15]
	s_mov_b32 m0, s38
	ds_read_b128 v[192:195], v156 offset:49152
	ds_read_b128 v[196:199], v156 offset:50176
	ds_read_b128 v[200:203], v156 offset:51200
	ds_read_b128 v[204:207], v156 offset:52224
	ds_read_b128 v[208:211], v156 offset:53248
	ds_read_b128 v[212:215], v156 offset:54272
	ds_read_b128 v[218:221], v156 offset:55296
	ds_read_b128 v[222:225], v156 offset:56320
	global_load_lds_dwordx4 v[152:153], off
	s_add_i32 m0, s38, 0x2000
	s_add_u32 s36, s36, 0x40080
	v_lshl_add_u64 v[152:153], v[226:227], 0, s[14:15]
	s_addc_u32 s37, s37, 0
	s_add_i32 s38, s71, s54
	global_load_lds_dwordx4 v[152:153], off
	v_lshl_add_u64 v[152:153], s[36:37], 0, v[132:133]
	s_mov_b32 m0, s38
	s_nop 0
	global_load_lds_dwordx4 v[152:153], off
	v_lshl_add_u64 v[152:153], s[36:37], 0, v[128:129]
	s_add_i32 m0, s38, 0x2000
	s_nop 0
	global_load_lds_dwordx4 v[152:153], off
	v_lshl_add_u64 v[152:153], v[228:229], 0, s[14:15]
	s_mov_b32 m0, s59
	s_nop 0
	global_load_lds_dwordx4 v[152:153], off
	v_lshl_add_u64 v[152:153], v[230:231], 0, s[14:15]
	s_mov_b32 m0, s60
	s_nop 0
	global_load_lds_dwordx4 v[152:153], off
	s_waitcnt vmcnt(8)
	s_waitcnt lgkmcnt(0)
	s_barrier
	s_setprio 1
	s_waitcnt lgkmcnt(0)
	v_mfma_f32_16x16x32_bf16 v[60:63], v[160:163], v[192:195], v[60:63]
	v_mfma_f32_16x16x32_bf16 v[56:59], v[168:171], v[192:195], v[56:59]
	v_mfma_f32_16x16x32_bf16 v[52:55], v[160:163], v[200:203], v[52:55]
	v_mfma_f32_16x16x32_bf16 v[44:47], v[168:171], v[200:203], v[44:47]
	v_mfma_f32_16x16x32_bf16 v[36:39], v[160:163], v[208:211], v[36:39]
	v_mfma_f32_16x16x32_bf16 v[28:31], v[168:171], v[208:211], v[28:31]
	v_mfma_f32_16x16x32_bf16 v[20:23], v[160:163], v[218:221], v[20:23]
	v_mfma_f32_16x16x32_bf16 v[12:15], v[168:171], v[218:221], v[12:15]
	v_mfma_f32_16x16x32_bf16 v[60:63], v[164:167], v[196:199], v[60:63]
	v_mfma_f32_16x16x32_bf16 v[56:59], v[172:175], v[196:199], v[56:59]
	v_mfma_f32_16x16x32_bf16 v[52:55], v[164:167], v[204:207], v[52:55]
	v_mfma_f32_16x16x32_bf16 v[44:47], v[172:175], v[204:207], v[44:47]
	v_mfma_f32_16x16x32_bf16 v[36:39], v[164:167], v[212:215], v[36:39]
	v_mfma_f32_16x16x32_bf16 v[28:31], v[172:175], v[212:215], v[28:31]
	v_mfma_f32_16x16x32_bf16 v[20:23], v[164:167], v[222:225], v[20:23]
	v_mfma_f32_16x16x32_bf16 v[12:15], v[172:175], v[222:225], v[12:15]
	v_mfma_f32_16x16x32_bf16 v[48:51], v[176:179], v[192:195], v[48:51]
	v_mfma_f32_16x16x32_bf16 v[40:43], v[184:187], v[192:195], v[40:43]
	v_mfma_f32_16x16x32_bf16 v[32:35], v[176:179], v[200:203], v[32:35]
	v_mfma_f32_16x16x32_bf16 v[24:27], v[184:187], v[200:203], v[24:27]
	v_mfma_f32_16x16x32_bf16 v[16:19], v[176:179], v[208:211], v[16:19]
	v_mfma_f32_16x16x32_bf16 v[8:11], v[184:187], v[208:211], v[8:11]
	v_mfma_f32_16x16x32_bf16 v[4:7], v[176:179], v[218:221], v[4:7]
	v_mfma_f32_16x16x32_bf16 v[0:3], v[184:187], v[218:221], v[0:3]
	v_mfma_f32_16x16x32_bf16 v[48:51], v[180:183], v[196:199], v[48:51]
	v_mfma_f32_16x16x32_bf16 v[40:43], v[188:191], v[196:199], v[40:43]
	v_mfma_f32_16x16x32_bf16 v[32:35], v[180:183], v[204:207], v[32:35]
	v_mfma_f32_16x16x32_bf16 v[24:27], v[188:191], v[204:207], v[24:27]
	v_mfma_f32_16x16x32_bf16 v[16:19], v[180:183], v[212:215], v[16:19]
	v_mfma_f32_16x16x32_bf16 v[8:11], v[188:191], v[212:215], v[8:11]
	v_mfma_f32_16x16x32_bf16 v[4:7], v[180:183], v[222:225], v[4:7]
	v_mfma_f32_16x16x32_bf16 v[0:3], v[188:191], v[222:225], v[0:3]
	s_setprio 0
	s_barrier
	s_add_i32 s68, s68, 2
	s_add_u32 s34, s34, 0x100
	s_addc_u32 s35, s35, 0
	s_add_u32 s66, s66, 0x100
	s_addc_u32 s67, s67, 0
	s_cmp_gt_u32 s68, 13
	s_cbranch_scc0 .LBB0_628
	s_and_b64 vcc, exec, s[16:17]
	s_cbranch_vccz .LBB0_631
	s_barrier

.Lzacc5a:
	s_waitcnt vmcnt(8)
	s_waitcnt lgkmcnt(0)
	s_barrier
	s_setprio 1
	s_waitcnt lgkmcnt(0)
	v_mfma_f32_16x16x32_bf16 v[132:135], v[112:115], v[160:163], v[132:135]
	v_mfma_f32_16x16x32_bf16 v[128:131], v[136:139], v[160:163], v[128:131]
	v_mfma_f32_16x16x32_bf16 v[108:111], v[112:115], v[168:171], v[108:111]
	v_mfma_f32_16x16x32_bf16 v[104:107], v[136:139], v[168:171], v[104:107]
	v_mfma_f32_16x16x32_bf16 v[92:95], v[112:115], v[176:179], v[92:95]
	v_mfma_f32_16x16x32_bf16 v[88:91], v[136:139], v[176:179], v[88:91]
	v_mfma_f32_16x16x32_bf16 v[76:79], v[112:115], v[200:203], v[76:79]
	v_mfma_f32_16x16x32_bf16 v[72:75], v[136:139], v[200:203], v[72:75]
	v_mfma_f32_16x16x32_bf16 v[132:135], v[124:127], v[164:167], v[132:135]
	v_mfma_f32_16x16x32_bf16 v[128:131], v[140:143], v[164:167], v[128:131]
	v_mfma_f32_16x16x32_bf16 v[108:111], v[124:127], v[172:175], v[108:111]
	v_mfma_f32_16x16x32_bf16 v[104:107], v[140:143], v[172:175], v[104:107]
	v_mfma_f32_16x16x32_bf16 v[92:95], v[124:127], v[180:183], v[92:95]
	v_mfma_f32_16x16x32_bf16 v[88:91], v[140:143], v[180:183], v[88:91]
	v_mfma_f32_16x16x32_bf16 v[76:79], v[124:127], v[204:207], v[76:79]
	v_mfma_f32_16x16x32_bf16 v[72:75], v[140:143], v[204:207], v[72:75]
	v_mfma_f32_16x16x32_bf16 v[120:123], v[144:147], v[160:163], v[120:123]
	v_mfma_f32_16x16x32_bf16 v[116:119], v[152:155], v[160:163], v[116:119]
	v_mfma_f32_16x16x32_bf16 v[100:103], v[144:147], v[168:171], v[100:103]
	v_mfma_f32_16x16x32_bf16 v[96:99], v[152:155], v[168:171], v[96:99]
	v_mfma_f32_16x16x32_bf16 v[84:87], v[144:147], v[176:179], v[84:87]
	v_mfma_f32_16x16x32_bf16 v[80:83], v[152:155], v[176:179], v[80:83]
	v_mfma_f32_16x16x32_bf16 v[68:71], v[144:147], v[200:203], v[68:71]
	v_mfma_f32_16x16x32_bf16 v[64:67], v[152:155], v[200:203], v[64:67]
	v_mfma_f32_16x16x32_bf16 v[120:123], v[148:151], v[164:167], v[120:123]
	v_mfma_f32_16x16x32_bf16 v[116:119], v[156:159], v[164:167], v[116:119]
	v_mfma_f32_16x16x32_bf16 v[100:103], v[148:151], v[172:175], v[100:103]
	v_mfma_f32_16x16x32_bf16 v[96:99], v[156:159], v[172:175], v[96:99]
	v_mfma_f32_16x16x32_bf16 v[84:87], v[148:151], v[180:183], v[84:87]
	v_mfma_f32_16x16x32_bf16 v[80:83], v[156:159], v[180:183], v[80:83]
	v_mfma_f32_16x16x32_bf16 v[68:71], v[148:151], v[204:207], v[68:71]
	v_mfma_f32_16x16x32_bf16 v[64:67], v[156:159], v[204:207], v[64:67]
	s_setprio 0
	s_barrier
	s_add_i32 s46, s77, s69
	v_lshl_add_u64 v[208:209], s[62:63], 0, v[186:187]
	s_mov_b32 m0, s46
	ds_read_b128 v[160:163], v225 offset:16384
	ds_read_b128 v[164:167], v225 offset:17408
	ds_read_b128 v[168:171], v225 offset:18432
	ds_read_b128 v[172:175], v225 offset:19456
	ds_read_b128 v[176:179], v225 offset:20480
	ds_read_b128 v[180:183], v225 offset:21504
	ds_read_b128 v[200:203], v225 offset:22528
	ds_read_b128 v[204:207], v225 offset:23552
	global_load_lds_dwordx4 v[208:209], off
	s_add_i32 m0, s46, 0x2000
	s_add_u32 s80, s62, 0x40000
	v_lshl_add_u64 v[210:211], s[62:63], 0, v[190:191]
	s_addc_u32 s81, s63, 0
	s_add_i32 s46, s78, s69
	global_load_lds_dwordx4 v[210:211], off
	v_lshl_add_u64 v[212:213], s[80:81], 0, v[186:187]
	s_mov_b32 m0, s46
	v_lshl_add_u64 v[214:215], s[64:65], 0, v[188:189]
	global_load_lds_dwordx4 v[212:213], off
	v_lshl_add_u64 v[212:213], s[80:81], 0, v[190:191]
	s_add_i32 m0, s46, 0x2000
	s_nop 0
	global_load_lds_dwordx4 v[212:213], off
	v_lshl_add_u64 v[212:213], s[64:65], 0, v[184:185]
	s_mov_b32 m0, s70
	s_nop 0
	global_load_lds_dwordx4 v[212:213], off
	s_mov_b32 m0, s71
	s_nop 0
	global_load_lds_dwordx4 v[214:215], off
	s_cmp_lg_u32 s59, -2
	s_cbranch_scc1 .Lzacc5b
	v_mov_b32_e32 v0, 0
	v_mov_b32_e32 v1, 0
	v_mov_b32_e32 v2, 0
	v_mov_b32_e32 v3, 0
	v_mov_b32_e32 v4, 0
	v_mov_b32_e32 v5, 0
	v_mov_b32_e32 v6, 0
	v_mov_b32_e32 v7, 0
	v_mov_b32_e32 v8, 0
	v_mov_b32_e32 v9, 0
	v_mov_b32_e32 v10, 0
	v_mov_b32_e32 v11, 0
	v_mov_b32_e32 v12, 0
	v_mov_b32_e32 v13, 0
	v_mov_b32_e32 v14, 0
	v_mov_b32_e32 v15, 0
	v_mov_b32_e32 v16, 0
	v_mov_b32_e32 v17, 0
	v_mov_b32_e32 v18, 0
	v_mov_b32_e32 v19, 0
	v_mov_b32_e32 v20, 0
	v_mov_b32_e32 v21, 0
	v_mov_b32_e32 v22, 0
	v_mov_b32_e32 v23, 0
	v_mov_b32_e32 v24, 0
	v_mov_b32_e32 v25, 0
	v_mov_b32_e32 v26, 0
	v_mov_b32_e32 v27, 0
	v_mov_b32_e32 v28, 0
	v_mov_b32_e32 v29, 0
	v_mov_b32_e32 v30, 0
	v_mov_b32_e32 v31, 0
	v_mov_b32_e32 v32, 0
	v_mov_b32_e32 v33, 0
	v_mov_b32_e32 v34, 0
	v_mov_b32_e32 v35, 0
	v_mov_b32_e32 v36, 0
	v_mov_b32_e32 v37, 0
	v_mov_b32_e32 v38, 0
	v_mov_b32_e32 v39, 0
	v_mov_b32_e32 v40, 0
	v_mov_b32_e32 v41, 0
	v_mov_b32_e32 v42, 0
	v_mov_b32_e32 v43, 0
	v_mov_b32_e32 v44, 0
	v_mov_b32_e32 v45, 0
	v_mov_b32_e32 v46, 0
	v_mov_b32_e32 v47, 0
	v_mov_b32_e32 v48, 0
	v_mov_b32_e32 v49, 0
	v_mov_b32_e32 v50, 0
	v_mov_b32_e32 v51, 0
	v_mov_b32_e32 v52, 0
	v_mov_b32_e32 v53, 0
	v_mov_b32_e32 v54, 0
	v_mov_b32_e32 v55, 0
	v_mov_b32_e32 v56, 0
	v_mov_b32_e32 v57, 0
	v_mov_b32_e32 v58, 0
	v_mov_b32_e32 v59, 0
	v_mov_b32_e32 v60, 0
	v_mov_b32_e32 v61, 0
	v_mov_b32_e32 v62, 0
	v_mov_b32_e32 v63, 0
.Lzacc5b:
	s_waitcnt vmcnt(8)
	s_waitcnt lgkmcnt(0)
	s_barrier
	s_setprio 1
	s_waitcnt lgkmcnt(0)
	v_mfma_f32_16x16x32_bf16 v[60:63], v[112:115], v[160:163], v[60:63]
	v_mfma_f32_16x16x32_bf16 v[56:59], v[136:139], v[160:163], v[56:59]
	v_mfma_f32_16x16x32_bf16 v[44:47], v[112:115], v[168:171], v[44:47]
	v_mfma_f32_16x16x32_bf16 v[40:43], v[136:139], v[168:171], v[40:43]
	v_mfma_f32_16x16x32_bf16 v[28:31], v[112:115], v[176:179], v[28:31]
	v_mfma_f32_16x16x32_bf16 v[24:27], v[136:139], v[176:179], v[24:27]
	v_mfma_f32_16x16x32_bf16 v[12:15], v[112:115], v[200:203], v[12:15]
	v_mfma_f32_16x16x32_bf16 v[8:11], v[136:139], v[200:203], v[8:11]
	v_mfma_f32_16x16x32_bf16 v[60:63], v[124:127], v[164:167], v[60:63]
	v_mfma_f32_16x16x32_bf16 v[56:59], v[140:143], v[164:167], v[56:59]
	v_mfma_f32_16x16x32_bf16 v[44:47], v[124:127], v[172:175], v[44:47]
	v_mfma_f32_16x16x32_bf16 v[40:43], v[140:143], v[172:175], v[40:43]
	v_mfma_f32_16x16x32_bf16 v[28:31], v[124:127], v[180:183], v[28:31]
	v_mfma_f32_16x16x32_bf16 v[24:27], v[140:143], v[180:183], v[24:27]
	v_mfma_f32_16x16x32_bf16 v[12:15], v[124:127], v[204:207], v[12:15]
	v_mfma_f32_16x16x32_bf16 v[8:11], v[140:143], v[204:207], v[8:11]
	v_mfma_f32_16x16x32_bf16 v[52:55], v[144:147], v[160:163], v[52:55]
	v_mfma_f32_16x16x32_bf16 v[48:51], v[152:155], v[160:163], v[48:51]
	v_mfma_f32_16x16x32_bf16 v[36:39], v[144:147], v[168:171], v[36:39]
	v_mfma_f32_16x16x32_bf16 v[32:35], v[152:155], v[168:171], v[32:35]
	v_mfma_f32_16x16x32_bf16 v[20:23], v[144:147], v[176:179], v[20:23]
	v_mfma_f32_16x16x32_bf16 v[16:19], v[152:155], v[176:179], v[16:19]
	v_mfma_f32_16x16x32_bf16 v[4:7], v[144:147], v[200:203], v[4:7]
	v_mfma_f32_16x16x32_bf16 v[0:3], v[152:155], v[200:203], v[0:3]
	v_mfma_f32_16x16x32_bf16 v[52:55], v[148:151], v[164:167], v[52:55]
	v_mfma_f32_16x16x32_bf16 v[48:51], v[156:159], v[164:167], v[48:51]
	v_mfma_f32_16x16x32_bf16 v[36:39], v[148:151], v[172:175], v[36:39]
	v_mfma_f32_16x16x32_bf16 v[32:35], v[156:159], v[172:175], v[32:35]
	v_mfma_f32_16x16x32_bf16 v[20:23], v[148:151], v[180:183], v[20:23]
	v_mfma_f32_16x16x32_bf16 v[16:19], v[156:159], v[180:183], v[16:19]
	v_mfma_f32_16x16x32_bf16 v[4:7], v[148:151], v[204:207], v[4:7]
	v_mfma_f32_16x16x32_bf16 v[0:3], v[156:159], v[204:207], v[0:3]
	s_setprio 0
	s_barrier
	s_add_i32 s46, 0, 0x18000
	s_add_i32 s47, 0, 0x1c000
	v_add_u32_e32 v140, s46, v220
	v_add_u32_e32 v156, s47, v220
	ds_read_b128 v[112:115], v140
	ds_read_b128 v[124:127], v140 offset:1024
	ds_read_b128 v[136:139], v140 offset:2048
	ds_read_b128 v[140:143], v140 offset:3072
	ds_read_b128 v[144:147], v156
	ds_read_b128 v[148:151], v156 offset:1024
	ds_read_b128 v[152:155], v156 offset:2048
	ds_read_b128 v[156:159], v156 offset:3072
	s_add_u32 s64, s64, 0x40000
	s_addc_u32 s65, s65, 0
	s_mov_b32 m0, s72
	v_lshl_add_u64 v[228:229], s[64:65], 0, v[184:185]
	ds_read_b128 v[160:163], v225 offset:32768
	ds_read_b128 v[164:167], v225 offset:33792
	ds_read_b128 v[168:171], v225 offset:34816
	ds_read_b128 v[172:175], v225 offset:35840
	ds_read_b128 v[176:179], v225 offset:36864
	ds_read_b128 v[180:183], v225 offset:37888
	ds_read_b128 v[200:203], v225 offset:38912
	ds_read_b128 v[204:207], v225 offset:39936
	global_load_lds_dwordx4 v[228:229], off
	v_lshl_add_u64 v[228:229], s[64:65], 0, v[188:189]
	s_mov_b32 m0, s73
	s_nop 0
	global_load_lds_dwordx4 v[228:229], off
	s_waitcnt vmcnt(8)
	s_waitcnt lgkmcnt(0)
	s_barrier
	s_setprio 1
	s_waitcnt lgkmcnt(0)
	v_mfma_f32_16x16x32_bf16 v[132:135], v[112:115], v[160:163], v[132:135]
	v_mfma_f32_16x16x32_bf16 v[128:131], v[136:139], v[160:163], v[128:131]
	v_mfma_f32_16x16x32_bf16 v[108:111], v[112:115], v[168:171], v[108:111]
	v_mfma_f32_16x16x32_bf16 v[104:107], v[136:139], v[168:171], v[104:107]
	v_mfma_f32_16x16x32_bf16 v[92:95], v[112:115], v[176:179], v[92:95]
	v_mfma_f32_16x16x32_bf16 v[88:91], v[136:139], v[176:179], v[88:91]
	v_mfma_f32_16x16x32_bf16 v[76:79], v[112:115], v[200:203], v[76:79]
	v_mfma_f32_16x16x32_bf16 v[72:75], v[136:139], v[200:203], v[72:75]
	v_mfma_f32_16x16x32_bf16 v[132:135], v[124:127], v[164:167], v[132:135]
	v_mfma_f32_16x16x32_bf16 v[128:131], v[140:143], v[164:167], v[128:131]
	v_mfma_f32_16x16x32_bf16 v[108:111], v[124:127], v[172:175], v[108:111]
	v_mfma_f32_16x16x32_bf16 v[104:107], v[140:143], v[172:175], v[104:107]
	v_mfma_f32_16x16x32_bf16 v[92:95], v[124:127], v[180:183], v[92:95]
	v_mfma_f32_16x16x32_bf16 v[88:91], v[140:143], v[180:183], v[88:91]
	v_mfma_f32_16x16x32_bf16 v[76:79], v[124:127], v[204:207], v[76:79]
	v_mfma_f32_16x16x32_bf16 v[72:75], v[140:143], v[204:207], v[72:75]
	v_mfma_f32_16x16x32_bf16 v[120:123], v[144:147], v[160:163], v[120:123]
	v_mfma_f32_16x16x32_bf16 v[116:119], v[152:155], v[160:163], v[116:119]
	v_mfma_f32_16x16x32_bf16 v[100:103], v[144:147], v[168:171], v[100:103]
	v_mfma_f32_16x16x32_bf16 v[96:99], v[152:155], v[168:171], v[96:99]
	v_mfma_f32_16x16x32_bf16 v[84:87], v[144:147], v[176:179], v[84:87]
	v_mfma_f32_16x16x32_bf16 v[80:83], v[152:155], v[176:179], v[80:83]
	v_mfma_f32_16x16x32_bf16 v[68:71], v[144:147], v[200:203], v[68:71]
	v_mfma_f32_16x16x32_bf16 v[64:67], v[152:155], v[200:203], v[64:67]
	v_mfma_f32_16x16x32_bf16 v[120:123], v[148:151], v[164:167], v[120:123]
	v_mfma_f32_16x16x32_bf16 v[116:119], v[156:159], v[164:167], v[116:119]
	v_mfma_f32_16x16x32_bf16 v[100:103], v[148:151], v[172:175], v[100:103]
	v_mfma_f32_16x16x32_bf16 v[96:99], v[156:159], v[172:175], v[96:99]
	v_mfma_f32_16x16x32_bf16 v[84:87], v[148:151], v[180:183], v[84:87]
	v_mfma_f32_16x16x32_bf16 v[80:83], v[156:159], v[180:183], v[80:83]
	v_mfma_f32_16x16x32_bf16 v[68:71], v[148:151], v[204:207], v[68:71]
	v_mfma_f32_16x16x32_bf16 v[64:67], v[156:159], v[204:207], v[64:67]
	s_setprio 0
	s_barrier
	s_add_i32 s46, s46, s69
	v_lshl_add_u64 v[208:209], v[208:209], 0, s[22:23]
	s_mov_b32 m0, s46
	ds_read_b128 v[160:163], v225 offset:49152
	ds_read_b128 v[164:167], v225 offset:50176
	ds_read_b128 v[168:171], v225 offset:51200
	ds_read_b128 v[172:175], v225 offset:52224
	ds_read_b128 v[176:179], v225 offset:53248
	ds_read_b128 v[180:183], v225 offset:54272
	ds_read_b128 v[200:203], v225 offset:55296
	ds_read_b128 v[204:207], v225 offset:56320
	global_load_lds_dwordx4 v[208:209], off
	s_add_i32 m0, s46, 0x2000
	s_add_u32 s62, s62, 0x40080
	v_lshl_add_u64 v[208:209], v[210:211], 0, s[22:23]
	s_addc_u32 s63, s63, 0
	s_add_i32 s46, s47, s69
	global_load_lds_dwordx4 v[208:209], off
	v_lshl_add_u64 v[208:209], s[62:63], 0, v[186:187]
	s_mov_b32 m0, s46
	s_nop 0
	global_load_lds_dwordx4 v[208:209], off
	v_lshl_add_u64 v[208:209], s[62:63], 0, v[190:191]
	s_add_i32 m0, s46, 0x2000
	s_nop 0
	global_load_lds_dwordx4 v[208:209], off
	v_lshl_add_u64 v[208:209], v[212:213], 0, s[22:23]
	s_mov_b32 m0, s51
	s_nop 0
	global_load_lds_dwordx4 v[208:209], off
	v_lshl_add_u64 v[208:209], v[214:215], 0, s[22:23]
	s_mov_b32 m0, s75
	s_nop 0
	global_load_lds_dwordx4 v[208:209], off
	s_waitcnt vmcnt(8)
	s_waitcnt lgkmcnt(0)
	s_barrier
	s_setprio 1
	s_waitcnt lgkmcnt(0)
	v_mfma_f32_16x16x32_bf16 v[60:63], v[112:115], v[160:163], v[60:63]
	v_mfma_f32_16x16x32_bf16 v[56:59], v[136:139], v[160:163], v[56:59]
	v_mfma_f32_16x16x32_bf16 v[44:47], v[112:115], v[168:171], v[44:47]
	v_mfma_f32_16x16x32_bf16 v[40:43], v[136:139], v[168:171], v[40:43]
	v_mfma_f32_16x16x32_bf16 v[28:31], v[112:115], v[176:179], v[28:31]
	v_mfma_f32_16x16x32_bf16 v[24:27], v[136:139], v[176:179], v[24:27]
	v_mfma_f32_16x16x32_bf16 v[12:15], v[112:115], v[200:203], v[12:15]
	v_mfma_f32_16x16x32_bf16 v[8:11], v[136:139], v[200:203], v[8:11]
	v_mfma_f32_16x16x32_bf16 v[60:63], v[124:127], v[164:167], v[60:63]
	v_mfma_f32_16x16x32_bf16 v[56:59], v[140:143], v[164:167], v[56:59]
	v_mfma_f32_16x16x32_bf16 v[44:47], v[124:127], v[172:175], v[44:47]
	v_mfma_f32_16x16x32_bf16 v[40:43], v[140:143], v[172:175], v[40:43]
	v_mfma_f32_16x16x32_bf16 v[28:31], v[124:127], v[180:183], v[28:31]
	v_mfma_f32_16x16x32_bf16 v[24:27], v[140:143], v[180:183], v[24:27]
	v_mfma_f32_16x16x32_bf16 v[12:15], v[124:127], v[204:207], v[12:15]
	v_mfma_f32_16x16x32_bf16 v[8:11], v[140:143], v[204:207], v[8:11]
	v_mfma_f32_16x16x32_bf16 v[52:55], v[144:147], v[160:163], v[52:55]
	v_mfma_f32_16x16x32_bf16 v[48:51], v[152:155], v[160:163], v[48:51]
	v_mfma_f32_16x16x32_bf16 v[36:39], v[144:147], v[168:171], v[36:39]
	v_mfma_f32_16x16x32_bf16 v[32:35], v[152:155], v[168:171], v[32:35]
	v_mfma_f32_16x16x32_bf16 v[20:23], v[144:147], v[176:179], v[20:23]
	v_mfma_f32_16x16x32_bf16 v[16:19], v[152:155], v[176:179], v[16:19]
	v_mfma_f32_16x16x32_bf16 v[4:7], v[144:147], v[200:203], v[4:7]
	v_mfma_f32_16x16x32_bf16 v[0:3], v[152:155], v[200:203], v[0:3]
	v_mfma_f32_16x16x32_bf16 v[52:55], v[148:151], v[164:167], v[52:55]
	v_mfma_f32_16x16x32_bf16 v[48:51], v[156:159], v[164:167], v[48:51]
	v_mfma_f32_16x16x32_bf16 v[36:39], v[148:151], v[172:175], v[36:39]
	v_mfma_f32_16x16x32_bf16 v[32:35], v[156:159], v[172:175], v[32:35]
	v_mfma_f32_16x16x32_bf16 v[20:23], v[148:151], v[180:183], v[20:23]
	v_mfma_f32_16x16x32_bf16 v[16:19], v[156:159], v[180:183], v[16:19]
	v_mfma_f32_16x16x32_bf16 v[4:7], v[148:151], v[204:207], v[4:7]
	v_mfma_f32_16x16x32_bf16 v[0:3], v[156:159], v[204:207], v[0:3]
	s_setprio 0
	s_barrier
	s_add_i32 s59, s59, 2
	s_add_u32 s60, s60, 0x100
	s_addc_u32 s61, s61, 0
	s_add_u32 s54, s54, 0x100
	s_addc_u32 s55, s55, 0
	s_cmp_gt_u32 s59, 13
	s_cbranch_scc0 .LBB0_904
	s_and_b64 vcc, exec, s[24:25]
	s_cbranch_vccz .LBB0_907
	s_barrier

.Lzacc6a:
	s_waitcnt vmcnt(8)
	s_waitcnt lgkmcnt(0)
	s_barrier
	s_setprio 1
	s_waitcnt lgkmcnt(0)
	v_mfma_f32_16x16x32_bf16 v[124:127], v[128:131], v[160:163], v[124:127]
	v_mfma_f32_16x16x32_bf16 v[120:123], v[136:139], v[160:163], v[120:123]
	v_mfma_f32_16x16x32_bf16 v[116:119], v[128:131], v[186:189], v[116:119]
	v_mfma_f32_16x16x32_bf16 v[112:115], v[136:139], v[186:189], v[112:115]
	v_mfma_f32_16x16x32_bf16 v[108:111], v[128:131], v[194:197], v[108:111]
	v_mfma_f32_16x16x32_bf16 v[104:107], v[136:139], v[194:197], v[104:107]
	v_mfma_f32_16x16x32_bf16 v[92:95], v[128:131], v[210:213], v[92:95]
	v_mfma_f32_16x16x32_bf16 v[84:87], v[136:139], v[210:213], v[84:87]
	v_mfma_f32_16x16x32_bf16 v[124:127], v[132:135], v[164:167], v[124:127]
	v_mfma_f32_16x16x32_bf16 v[120:123], v[140:143], v[164:167], v[120:123]
	v_mfma_f32_16x16x32_bf16 v[116:119], v[132:135], v[190:193], v[116:119]
	v_mfma_f32_16x16x32_bf16 v[112:115], v[140:143], v[190:193], v[112:115]
	v_mfma_f32_16x16x32_bf16 v[108:111], v[132:135], v[198:201], v[108:111]
	v_mfma_f32_16x16x32_bf16 v[104:107], v[140:143], v[198:201], v[104:107]
	v_mfma_f32_16x16x32_bf16 v[92:95], v[132:135], v[218:221], v[92:95]
	v_mfma_f32_16x16x32_bf16 v[84:87], v[140:143], v[218:221], v[84:87]
	v_mfma_f32_16x16x32_bf16 v[88:91], v[144:147], v[160:163], v[88:91]
	v_mfma_f32_16x16x32_bf16 v[24:27], v[152:155], v[160:163], v[24:27]
	v_mfma_f32_16x16x32_bf16 v[100:103], v[144:147], v[186:189], v[100:103]
	v_mfma_f32_16x16x32_bf16 v[36:39], v[152:155], v[186:189], v[36:39]
	v_mfma_f32_16x16x32_bf16 v[96:99], v[144:147], v[194:197], v[96:99]
	v_mfma_f32_16x16x32_bf16 v[52:55], v[152:155], v[194:197], v[52:55]
	v_mfma_f32_16x16x32_bf16 v[80:83], v[144:147], v[210:213], v[80:83]
	v_mfma_f32_16x16x32_bf16 v[64:67], v[152:155], v[210:213], v[64:67]
	v_mfma_f32_16x16x32_bf16 v[88:91], v[148:151], v[164:167], v[88:91]
	v_mfma_f32_16x16x32_bf16 v[24:27], v[156:159], v[164:167], v[24:27]
	v_mfma_f32_16x16x32_bf16 v[100:103], v[148:151], v[190:193], v[100:103]
	v_mfma_f32_16x16x32_bf16 v[36:39], v[156:159], v[190:193], v[36:39]
	v_mfma_f32_16x16x32_bf16 v[96:99], v[148:151], v[198:201], v[96:99]
	v_mfma_f32_16x16x32_bf16 v[52:55], v[156:159], v[198:201], v[52:55]
	v_mfma_f32_16x16x32_bf16 v[80:83], v[148:151], v[218:221], v[80:83]
	v_mfma_f32_16x16x32_bf16 v[64:67], v[156:159], v[218:221], v[64:67]
	s_setprio 0
	s_barrier
	s_add_i32 s46, s82, s66
	v_lshl_add_u64 v[214:215], s[10:11], 0, v[172:173]
	s_mov_b32 m0, s46
	ds_read_b128 v[160:163], v206 offset:16384
	ds_read_b128 v[164:167], v206 offset:17408
	ds_read_b128 v[186:189], v206 offset:18432
	ds_read_b128 v[190:193], v206 offset:19456
	ds_read_b128 v[194:197], v206 offset:20480
	ds_read_b128 v[198:201], v206 offset:21504
	ds_read_b128 v[210:213], v206 offset:22528
	ds_read_b128 v[218:221], v206 offset:23552
	global_load_lds_dwordx4 v[214:215], off
	s_add_i32 m0, s46, 0x2000
	s_add_u32 s92, s10, 0x40000
	v_lshl_add_u64 v[222:223], s[10:11], 0, v[168:169]
	s_addc_u32 s93, s11, 0
	s_add_i32 s46, s83, s66
	global_load_lds_dwordx4 v[222:223], off
	v_lshl_add_u64 v[224:225], s[92:93], 0, v[172:173]
	s_mov_b32 m0, s46
	v_lshl_add_u64 v[226:227], s[14:15], 0, v[170:171]
	global_load_lds_dwordx4 v[224:225], off
	v_lshl_add_u64 v[224:225], s[92:93], 0, v[168:169]
	s_add_i32 m0, s46, 0x2000
	s_nop 0
	global_load_lds_dwordx4 v[224:225], off
	v_lshl_add_u64 v[224:225], s[14:15], 0, v[174:175]
	s_mov_b32 m0, s53
	s_nop 0
	global_load_lds_dwordx4 v[224:225], off
	s_mov_b32 m0, s67
	s_nop 0
	global_load_lds_dwordx4 v[226:227], off
	s_cmp_lg_u32 s60, -2
	s_cbranch_scc1 .Lzacc6b
	v_mov_b32_e32 v0, 0
	v_mov_b32_e32 v1, 0
	v_mov_b32_e32 v2, 0
	v_mov_b32_e32 v3, 0
	v_mov_b32_e32 v4, 0
	v_mov_b32_e32 v5, 0
	v_mov_b32_e32 v6, 0
	v_mov_b32_e32 v7, 0
	v_mov_b32_e32 v8, 0
	v_mov_b32_e32 v9, 0
	v_mov_b32_e32 v10, 0
	v_mov_b32_e32 v11, 0
	v_mov_b32_e32 v12, 0
	v_mov_b32_e32 v13, 0
	v_mov_b32_e32 v14, 0
	v_mov_b32_e32 v15, 0
	v_mov_b32_e32 v16, 0
	v_mov_b32_e32 v17, 0
	v_mov_b32_e32 v18, 0
	v_mov_b32_e32 v19, 0
	v_mov_b32_e32 v20, 0
	v_mov_b32_e32 v21, 0
	v_mov_b32_e32 v22, 0
	v_mov_b32_e32 v23, 0
	v_mov_b32_e32 v28, 0
	v_mov_b32_e32 v29, 0
	v_mov_b32_e32 v30, 0
	v_mov_b32_e32 v31, 0
	v_mov_b32_e32 v32, 0
	v_mov_b32_e32 v33, 0
	v_mov_b32_e32 v34, 0
	v_mov_b32_e32 v35, 0
	v_mov_b32_e32 v40, 0
	v_mov_b32_e32 v41, 0
	v_mov_b32_e32 v42, 0
	v_mov_b32_e32 v43, 0
	v_mov_b32_e32 v44, 0
	v_mov_b32_e32 v45, 0
	v_mov_b32_e32 v46, 0
	v_mov_b32_e32 v47, 0
	v_mov_b32_e32 v48, 0
	v_mov_b32_e32 v49, 0
	v_mov_b32_e32 v50, 0
	v_mov_b32_e32 v51, 0
	v_mov_b32_e32 v56, 0
	v_mov_b32_e32 v57, 0
	v_mov_b32_e32 v58, 0
	v_mov_b32_e32 v59, 0
	v_mov_b32_e32 v60, 0
	v_mov_b32_e32 v61, 0
	v_mov_b32_e32 v62, 0
	v_mov_b32_e32 v63, 0
	v_mov_b32_e32 v68, 0
	v_mov_b32_e32 v69, 0
	v_mov_b32_e32 v70, 0
	v_mov_b32_e32 v71, 0
	v_mov_b32_e32 v72, 0
	v_mov_b32_e32 v73, 0
	v_mov_b32_e32 v74, 0
	v_mov_b32_e32 v75, 0
	v_mov_b32_e32 v76, 0
	v_mov_b32_e32 v77, 0
	v_mov_b32_e32 v78, 0
	v_mov_b32_e32 v79, 0
.Lzacc6b:
	s_waitcnt vmcnt(8)
	s_waitcnt lgkmcnt(0)
	s_barrier
	s_setprio 1
	s_waitcnt lgkmcnt(0)
	v_mfma_f32_16x16x32_bf16 v[76:79], v[128:131], v[160:163], v[76:79]
	v_mfma_f32_16x16x32_bf16 v[72:75], v[136:139], v[160:163], v[72:75]
	v_mfma_f32_16x16x32_bf16 v[60:63], v[128:131], v[186:189], v[60:63]
	v_mfma_f32_16x16x32_bf16 v[56:59], v[136:139], v[186:189], v[56:59]
	v_mfma_f32_16x16x32_bf16 v[44:47], v[128:131], v[194:197], v[44:47]
	v_mfma_f32_16x16x32_bf16 v[40:43], v[136:139], v[194:197], v[40:43]
	v_mfma_f32_16x16x32_bf16 v[20:23], v[128:131], v[210:213], v[20:23]
	v_mfma_f32_16x16x32_bf16 v[8:11], v[136:139], v[210:213], v[8:11]
	v_mfma_f32_16x16x32_bf16 v[76:79], v[132:135], v[164:167], v[76:79]
	v_mfma_f32_16x16x32_bf16 v[72:75], v[140:143], v[164:167], v[72:75]
	v_mfma_f32_16x16x32_bf16 v[60:63], v[132:135], v[190:193], v[60:63]
	v_mfma_f32_16x16x32_bf16 v[56:59], v[140:143], v[190:193], v[56:59]
	v_mfma_f32_16x16x32_bf16 v[44:47], v[132:135], v[198:201], v[44:47]
	v_mfma_f32_16x16x32_bf16 v[40:43], v[140:143], v[198:201], v[40:43]
	v_mfma_f32_16x16x32_bf16 v[20:23], v[132:135], v[218:221], v[20:23]
	v_mfma_f32_16x16x32_bf16 v[8:11], v[140:143], v[218:221], v[8:11]
	v_mfma_f32_16x16x32_bf16 v[68:71], v[144:147], v[160:163], v[68:71]
	v_mfma_f32_16x16x32_bf16 v[12:15], v[152:155], v[160:163], v[12:15]
	v_mfma_f32_16x16x32_bf16 v[48:51], v[144:147], v[186:189], v[48:51]
	v_mfma_f32_16x16x32_bf16 v[28:31], v[152:155], v[186:189], v[28:31]
	v_mfma_f32_16x16x32_bf16 v[32:35], v[144:147], v[194:197], v[32:35]
	v_mfma_f32_16x16x32_bf16 v[16:19], v[152:155], v[194:197], v[16:19]
	v_mfma_f32_16x16x32_bf16 v[4:7], v[144:147], v[210:213], v[4:7]
	v_mfma_f32_16x16x32_bf16 v[0:3], v[152:155], v[210:213], v[0:3]
	v_mfma_f32_16x16x32_bf16 v[68:71], v[148:151], v[164:167], v[68:71]
	v_mfma_f32_16x16x32_bf16 v[12:15], v[156:159], v[164:167], v[12:15]
	v_mfma_f32_16x16x32_bf16 v[48:51], v[148:151], v[190:193], v[48:51]
	v_mfma_f32_16x16x32_bf16 v[28:31], v[156:159], v[190:193], v[28:31]
	v_mfma_f32_16x16x32_bf16 v[32:35], v[148:151], v[198:201], v[32:35]
	v_mfma_f32_16x16x32_bf16 v[16:19], v[156:159], v[198:201], v[16:19]
	v_mfma_f32_16x16x32_bf16 v[4:7], v[148:151], v[218:221], v[4:7]
	v_mfma_f32_16x16x32_bf16 v[0:3], v[156:159], v[218:221], v[0:3]
	s_setprio 0
	s_barrier
	s_add_i32 s46, 0, 0x18000
	s_add_i32 s47, 0, 0x1c000
	v_add_u32_e32 v140, s46, v203
	v_add_u32_e32 v156, s47, v203
	ds_read_b128 v[128:131], v140
	ds_read_b128 v[132:135], v140 offset:1024
	ds_read_b128 v[136:139], v140 offset:2048
	ds_read_b128 v[140:143], v140 offset:3072
	ds_read_b128 v[144:147], v156
	ds_read_b128 v[148:151], v156 offset:1024
	ds_read_b128 v[152:155], v156 offset:2048
	ds_read_b128 v[156:159], v156 offset:3072
	s_add_u32 s14, s14, 0x40000
	s_addc_u32 s15, s15, 0
	s_mov_b32 m0, s68
	v_lshl_add_u64 v[228:229], s[14:15], 0, v[174:175]
	ds_read_b128 v[160:163], v206 offset:32768
	ds_read_b128 v[164:167], v206 offset:33792
	ds_read_b128 v[186:189], v206 offset:34816
	ds_read_b128 v[190:193], v206 offset:35840
	ds_read_b128 v[194:197], v206 offset:36864
	ds_read_b128 v[198:201], v206 offset:37888
	ds_read_b128 v[210:213], v206 offset:38912
	ds_read_b128 v[218:221], v206 offset:39936
	global_load_lds_dwordx4 v[228:229], off
	v_lshl_add_u64 v[228:229], s[14:15], 0, v[170:171]
	s_mov_b32 m0, s69
	s_nop 0
	global_load_lds_dwordx4 v[228:229], off
	s_waitcnt vmcnt(8)
	s_waitcnt lgkmcnt(0)
	s_barrier
	s_setprio 1
	s_waitcnt lgkmcnt(0)
	v_mfma_f32_16x16x32_bf16 v[124:127], v[128:131], v[160:163], v[124:127]
	v_mfma_f32_16x16x32_bf16 v[120:123], v[136:139], v[160:163], v[120:123]
	v_mfma_f32_16x16x32_bf16 v[116:119], v[128:131], v[186:189], v[116:119]
	v_mfma_f32_16x16x32_bf16 v[112:115], v[136:139], v[186:189], v[112:115]
	v_mfma_f32_16x16x32_bf16 v[108:111], v[128:131], v[194:197], v[108:111]
	v_mfma_f32_16x16x32_bf16 v[104:107], v[136:139], v[194:197], v[104:107]
	v_mfma_f32_16x16x32_bf16 v[92:95], v[128:131], v[210:213], v[92:95]
	v_mfma_f32_16x16x32_bf16 v[84:87], v[136:139], v[210:213], v[84:87]
	v_mfma_f32_16x16x32_bf16 v[124:127], v[132:135], v[164:167], v[124:127]
	v_mfma_f32_16x16x32_bf16 v[120:123], v[140:143], v[164:167], v[120:123]
	v_mfma_f32_16x16x32_bf16 v[116:119], v[132:135], v[190:193], v[116:119]
	v_mfma_f32_16x16x32_bf16 v[112:115], v[140:143], v[190:193], v[112:115]
	v_mfma_f32_16x16x32_bf16 v[108:111], v[132:135], v[198:201], v[108:111]
	v_mfma_f32_16x16x32_bf16 v[104:107], v[140:143], v[198:201], v[104:107]
	v_mfma_f32_16x16x32_bf16 v[92:95], v[132:135], v[218:221], v[92:95]
	v_mfma_f32_16x16x32_bf16 v[84:87], v[140:143], v[218:221], v[84:87]
	v_mfma_f32_16x16x32_bf16 v[88:91], v[144:147], v[160:163], v[88:91]
	v_mfma_f32_16x16x32_bf16 v[24:27], v[152:155], v[160:163], v[24:27]
	v_mfma_f32_16x16x32_bf16 v[100:103], v[144:147], v[186:189], v[100:103]
	v_mfma_f32_16x16x32_bf16 v[36:39], v[152:155], v[186:189], v[36:39]
	v_mfma_f32_16x16x32_bf16 v[96:99], v[144:147], v[194:197], v[96:99]
	v_mfma_f32_16x16x32_bf16 v[52:55], v[152:155], v[194:197], v[52:55]
	v_mfma_f32_16x16x32_bf16 v[80:83], v[144:147], v[210:213], v[80:83]
	v_mfma_f32_16x16x32_bf16 v[64:67], v[152:155], v[210:213], v[64:67]
	v_mfma_f32_16x16x32_bf16 v[88:91], v[148:151], v[164:167], v[88:91]
	v_mfma_f32_16x16x32_bf16 v[24:27], v[156:159], v[164:167], v[24:27]
	v_mfma_f32_16x16x32_bf16 v[100:103], v[148:151], v[190:193], v[100:103]
	v_mfma_f32_16x16x32_bf16 v[36:39], v[156:159], v[190:193], v[36:39]
	v_mfma_f32_16x16x32_bf16 v[96:99], v[148:151], v[198:201], v[96:99]
	v_mfma_f32_16x16x32_bf16 v[52:55], v[156:159], v[198:201], v[52:55]
	v_mfma_f32_16x16x32_bf16 v[80:83], v[148:151], v[218:221], v[80:83]
	v_mfma_f32_16x16x32_bf16 v[64:67], v[156:159], v[218:221], v[64:67]
	s_setprio 0
	s_barrier
	s_add_i32 s14, s46, s66
	v_lshl_add_u64 v[214:215], v[214:215], 0, s[26:27]
	s_mov_b32 m0, s14
	ds_read_b128 v[160:163], v206 offset:49152
	ds_read_b128 v[164:167], v206 offset:50176
	ds_read_b128 v[186:189], v206 offset:51200
	ds_read_b128 v[190:193], v206 offset:52224
	ds_read_b128 v[194:197], v206 offset:53248
	ds_read_b128 v[198:201], v206 offset:54272
	ds_read_b128 v[210:213], v206 offset:55296
	ds_read_b128 v[218:221], v206 offset:56320
	global_load_lds_dwordx4 v[214:215], off
	s_add_i32 m0, s14, 0x2000
	s_add_u32 s10, s10, 0x40080
	v_lshl_add_u64 v[214:215], v[222:223], 0, s[26:27]
	s_addc_u32 s11, s11, 0
	s_add_i32 s14, s47, s66
	global_load_lds_dwordx4 v[214:215], off
	v_lshl_add_u64 v[214:215], s[10:11], 0, v[172:173]
	s_mov_b32 m0, s14
	s_nop 0
	global_load_lds_dwordx4 v[214:215], off
	v_lshl_add_u64 v[214:215], s[10:11], 0, v[168:169]
	s_add_i32 m0, s14, 0x2000
	s_nop 0
	global_load_lds_dwordx4 v[214:215], off
	v_lshl_add_u64 v[214:215], v[224:225], 0, s[26:27]
	s_mov_b32 m0, s75
	s_nop 0
	global_load_lds_dwordx4 v[214:215], off
	v_lshl_add_u64 v[214:215], v[226:227], 0, s[26:27]
	s_mov_b32 m0, s76
	s_nop 0
	global_load_lds_dwordx4 v[214:215], off
	s_waitcnt vmcnt(8)
	s_waitcnt lgkmcnt(0)
	s_barrier
	s_setprio 1
	s_waitcnt lgkmcnt(0)
	v_mfma_f32_16x16x32_bf16 v[76:79], v[128:131], v[160:163], v[76:79]
	v_mfma_f32_16x16x32_bf16 v[72:75], v[136:139], v[160:163], v[72:75]
	v_mfma_f32_16x16x32_bf16 v[60:63], v[128:131], v[186:189], v[60:63]
	v_mfma_f32_16x16x32_bf16 v[56:59], v[136:139], v[186:189], v[56:59]
	v_mfma_f32_16x16x32_bf16 v[44:47], v[128:131], v[194:197], v[44:47]
	v_mfma_f32_16x16x32_bf16 v[40:43], v[136:139], v[194:197], v[40:43]
	v_mfma_f32_16x16x32_bf16 v[20:23], v[128:131], v[210:213], v[20:23]
	v_mfma_f32_16x16x32_bf16 v[8:11], v[136:139], v[210:213], v[8:11]
	v_mfma_f32_16x16x32_bf16 v[76:79], v[132:135], v[164:167], v[76:79]
	v_mfma_f32_16x16x32_bf16 v[72:75], v[140:143], v[164:167], v[72:75]
	v_mfma_f32_16x16x32_bf16 v[60:63], v[132:135], v[190:193], v[60:63]
	v_mfma_f32_16x16x32_bf16 v[56:59], v[140:143], v[190:193], v[56:59]
	v_mfma_f32_16x16x32_bf16 v[44:47], v[132:135], v[198:201], v[44:47]
	v_mfma_f32_16x16x32_bf16 v[40:43], v[140:143], v[198:201], v[40:43]
	v_mfma_f32_16x16x32_bf16 v[20:23], v[132:135], v[218:221], v[20:23]
	v_mfma_f32_16x16x32_bf16 v[8:11], v[140:143], v[218:221], v[8:11]
	v_mfma_f32_16x16x32_bf16 v[68:71], v[144:147], v[160:163], v[68:71]
	v_mfma_f32_16x16x32_bf16 v[12:15], v[152:155], v[160:163], v[12:15]
	v_mfma_f32_16x16x32_bf16 v[48:51], v[144:147], v[186:189], v[48:51]
	v_mfma_f32_16x16x32_bf16 v[28:31], v[152:155], v[186:189], v[28:31]
	v_mfma_f32_16x16x32_bf16 v[32:35], v[144:147], v[194:197], v[32:35]
	v_mfma_f32_16x16x32_bf16 v[16:19], v[152:155], v[194:197], v[16:19]
	v_mfma_f32_16x16x32_bf16 v[4:7], v[144:147], v[210:213], v[4:7]
	v_mfma_f32_16x16x32_bf16 v[0:3], v[152:155], v[210:213], v[0:3]
	v_mfma_f32_16x16x32_bf16 v[68:71], v[148:151], v[164:167], v[68:71]
	v_mfma_f32_16x16x32_bf16 v[12:15], v[156:159], v[164:167], v[12:15]
	v_mfma_f32_16x16x32_bf16 v[48:51], v[148:151], v[190:193], v[48:51]
	v_mfma_f32_16x16x32_bf16 v[28:31], v[156:159], v[190:193], v[28:31]
	v_mfma_f32_16x16x32_bf16 v[32:35], v[148:151], v[198:201], v[32:35]
	v_mfma_f32_16x16x32_bf16 v[16:19], v[156:159], v[198:201], v[16:19]
	v_mfma_f32_16x16x32_bf16 v[4:7], v[148:151], v[218:221], v[4:7]
	v_mfma_f32_16x16x32_bf16 v[0:3], v[156:159], v[218:221], v[0:3]
	s_setprio 0
	s_barrier
	s_add_i32 s60, s60, 2
	s_add_u32 s8, s8, 0x100
	s_addc_u32 s9, s9, 0
	s_add_u32 s51, s51, 0x100
	s_addc_u32 s55, s55, 0
	s_cmp_gt_u32 s60, 13
	s_cbranch_scc0 .LBB0_991
	s_and_b64 vcc, exec, s[30:31]
	s_cbranch_vccz .LBB0_994
	s_barrier

.Lzacc7a:
	s_waitcnt vmcnt(8)
	s_waitcnt lgkmcnt(0)
	s_barrier
	s_setprio 1
	s_waitcnt lgkmcnt(0)
	v_mfma_f32_16x16x32_bf16 v[132:135], v[112:115], v[160:163], v[132:135]
	v_mfma_f32_16x16x32_bf16 v[128:131], v[136:139], v[160:163], v[128:131]
	v_mfma_f32_16x16x32_bf16 v[108:111], v[112:115], v[168:171], v[108:111]
	v_mfma_f32_16x16x32_bf16 v[104:107], v[136:139], v[168:171], v[104:107]
	v_mfma_f32_16x16x32_bf16 v[92:95], v[112:115], v[176:179], v[92:95]
	v_mfma_f32_16x16x32_bf16 v[88:91], v[136:139], v[176:179], v[88:91]
	v_mfma_f32_16x16x32_bf16 v[76:79], v[112:115], v[200:203], v[76:79]
	v_mfma_f32_16x16x32_bf16 v[72:75], v[136:139], v[200:203], v[72:75]
	v_mfma_f32_16x16x32_bf16 v[132:135], v[124:127], v[164:167], v[132:135]
	v_mfma_f32_16x16x32_bf16 v[128:131], v[140:143], v[164:167], v[128:131]
	v_mfma_f32_16x16x32_bf16 v[108:111], v[124:127], v[172:175], v[108:111]
	v_mfma_f32_16x16x32_bf16 v[104:107], v[140:143], v[172:175], v[104:107]
	v_mfma_f32_16x16x32_bf16 v[92:95], v[124:127], v[180:183], v[92:95]
	v_mfma_f32_16x16x32_bf16 v[88:91], v[140:143], v[180:183], v[88:91]
	v_mfma_f32_16x16x32_bf16 v[76:79], v[124:127], v[204:207], v[76:79]
	v_mfma_f32_16x16x32_bf16 v[72:75], v[140:143], v[204:207], v[72:75]
	v_mfma_f32_16x16x32_bf16 v[120:123], v[144:147], v[160:163], v[120:123]
	v_mfma_f32_16x16x32_bf16 v[116:119], v[152:155], v[160:163], v[116:119]
	v_mfma_f32_16x16x32_bf16 v[100:103], v[144:147], v[168:171], v[100:103]
	v_mfma_f32_16x16x32_bf16 v[96:99], v[152:155], v[168:171], v[96:99]
	v_mfma_f32_16x16x32_bf16 v[84:87], v[144:147], v[176:179], v[84:87]
	v_mfma_f32_16x16x32_bf16 v[80:83], v[152:155], v[176:179], v[80:83]
	v_mfma_f32_16x16x32_bf16 v[68:71], v[144:147], v[200:203], v[68:71]
	v_mfma_f32_16x16x32_bf16 v[64:67], v[152:155], v[200:203], v[64:67]
	v_mfma_f32_16x16x32_bf16 v[120:123], v[148:151], v[164:167], v[120:123]
	v_mfma_f32_16x16x32_bf16 v[116:119], v[156:159], v[164:167], v[116:119]
	v_mfma_f32_16x16x32_bf16 v[100:103], v[148:151], v[172:175], v[100:103]
	v_mfma_f32_16x16x32_bf16 v[96:99], v[156:159], v[172:175], v[96:99]
	v_mfma_f32_16x16x32_bf16 v[84:87], v[148:151], v[180:183], v[84:87]
	v_mfma_f32_16x16x32_bf16 v[80:83], v[156:159], v[180:183], v[80:83]
	v_mfma_f32_16x16x32_bf16 v[68:71], v[148:151], v[204:207], v[68:71]
	v_mfma_f32_16x16x32_bf16 v[64:67], v[156:159], v[204:207], v[64:67]
	s_setprio 0
	s_barrier
	s_add_i32 s36, s63, s54
	v_lshl_add_u64 v[208:209], s[46:47], 0, v[186:187]
	s_mov_b32 m0, s36
	ds_read_b128 v[160:163], v225 offset:16384
	ds_read_b128 v[164:167], v225 offset:17408
	ds_read_b128 v[168:171], v225 offset:18432
	ds_read_b128 v[172:175], v225 offset:19456
	ds_read_b128 v[176:179], v225 offset:20480
	ds_read_b128 v[180:183], v225 offset:21504
	ds_read_b128 v[200:203], v225 offset:22528
	ds_read_b128 v[204:207], v225 offset:23552
	global_load_lds_dwordx4 v[208:209], off
	s_add_i32 m0, s36, 0x2000
	s_add_u32 s36, s46, 0xb0000
	v_lshl_add_u64 v[210:211], s[46:47], 0, v[190:191]
	s_addc_u32 s37, s47, 0
	s_add_i32 s72, s64, s54
	global_load_lds_dwordx4 v[210:211], off
	v_lshl_add_u64 v[212:213], s[36:37], 0, v[186:187]
	s_mov_b32 m0, s72
	v_lshl_add_u64 v[214:215], s[48:49], 0, v[188:189]
	global_load_lds_dwordx4 v[212:213], off
	v_lshl_add_u64 v[212:213], s[36:37], 0, v[190:191]
	s_add_i32 m0, s72, 0x2000
	s_nop 0
	global_load_lds_dwordx4 v[212:213], off
	v_lshl_add_u64 v[212:213], s[48:49], 0, v[184:185]
	s_mov_b32 m0, s55
	s_nop 0
	global_load_lds_dwordx4 v[212:213], off
	s_mov_b32 m0, s56
	s_nop 0
	global_load_lds_dwordx4 v[214:215], off
	s_cmp_lg_u32 s71, -2
	s_cbranch_scc1 .Lzacc7b
	v_mov_b32_e32 v0, 0
	v_mov_b32_e32 v1, 0
	v_mov_b32_e32 v2, 0
	v_mov_b32_e32 v3, 0
	v_mov_b32_e32 v4, 0
	v_mov_b32_e32 v5, 0
	v_mov_b32_e32 v6, 0
	v_mov_b32_e32 v7, 0
	v_mov_b32_e32 v8, 0
	v_mov_b32_e32 v9, 0
	v_mov_b32_e32 v10, 0
	v_mov_b32_e32 v11, 0
	v_mov_b32_e32 v12, 0
	v_mov_b32_e32 v13, 0
	v_mov_b32_e32 v14, 0
	v_mov_b32_e32 v15, 0
	v_mov_b32_e32 v16, 0
	v_mov_b32_e32 v17, 0
	v_mov_b32_e32 v18, 0
	v_mov_b32_e32 v19, 0
	v_mov_b32_e32 v20, 0
	v_mov_b32_e32 v21, 0
	v_mov_b32_e32 v22, 0
	v_mov_b32_e32 v23, 0
	v_mov_b32_e32 v24, 0
	v_mov_b32_e32 v25, 0
	v_mov_b32_e32 v26, 0
	v_mov_b32_e32 v27, 0
	v_mov_b32_e32 v28, 0
	v_mov_b32_e32 v29, 0
	v_mov_b32_e32 v30, 0
	v_mov_b32_e32 v31, 0
	v_mov_b32_e32 v32, 0
	v_mov_b32_e32 v33, 0
	v_mov_b32_e32 v34, 0
	v_mov_b32_e32 v35, 0
	v_mov_b32_e32 v36, 0
	v_mov_b32_e32 v37, 0
	v_mov_b32_e32 v38, 0
	v_mov_b32_e32 v39, 0
	v_mov_b32_e32 v40, 0
	v_mov_b32_e32 v41, 0
	v_mov_b32_e32 v42, 0
	v_mov_b32_e32 v43, 0
	v_mov_b32_e32 v44, 0
	v_mov_b32_e32 v45, 0
	v_mov_b32_e32 v46, 0
	v_mov_b32_e32 v47, 0
	v_mov_b32_e32 v48, 0
	v_mov_b32_e32 v49, 0
	v_mov_b32_e32 v50, 0
	v_mov_b32_e32 v51, 0
	v_mov_b32_e32 v52, 0
	v_mov_b32_e32 v53, 0
	v_mov_b32_e32 v54, 0
	v_mov_b32_e32 v55, 0
	v_mov_b32_e32 v56, 0
	v_mov_b32_e32 v57, 0
	v_mov_b32_e32 v58, 0
	v_mov_b32_e32 v59, 0
	v_mov_b32_e32 v60, 0
	v_mov_b32_e32 v61, 0
	v_mov_b32_e32 v62, 0
	v_mov_b32_e32 v63, 0
.Lzacc7b:
	s_waitcnt vmcnt(8)
	s_waitcnt lgkmcnt(0)
	s_barrier
	s_setprio 1
	s_waitcnt lgkmcnt(0)
	v_mfma_f32_16x16x32_bf16 v[60:63], v[112:115], v[160:163], v[60:63]
	v_mfma_f32_16x16x32_bf16 v[56:59], v[136:139], v[160:163], v[56:59]
	v_mfma_f32_16x16x32_bf16 v[44:47], v[112:115], v[168:171], v[44:47]
	v_mfma_f32_16x16x32_bf16 v[40:43], v[136:139], v[168:171], v[40:43]
	v_mfma_f32_16x16x32_bf16 v[28:31], v[112:115], v[176:179], v[28:31]
	v_mfma_f32_16x16x32_bf16 v[24:27], v[136:139], v[176:179], v[24:27]
	v_mfma_f32_16x16x32_bf16 v[12:15], v[112:115], v[200:203], v[12:15]
	v_mfma_f32_16x16x32_bf16 v[8:11], v[136:139], v[200:203], v[8:11]
	v_mfma_f32_16x16x32_bf16 v[60:63], v[124:127], v[164:167], v[60:63]
	v_mfma_f32_16x16x32_bf16 v[56:59], v[140:143], v[164:167], v[56:59]
	v_mfma_f32_16x16x32_bf16 v[44:47], v[124:127], v[172:175], v[44:47]
	v_mfma_f32_16x16x32_bf16 v[40:43], v[140:143], v[172:175], v[40:43]
	v_mfma_f32_16x16x32_bf16 v[28:31], v[124:127], v[180:183], v[28:31]
	v_mfma_f32_16x16x32_bf16 v[24:27], v[140:143], v[180:183], v[24:27]
	v_mfma_f32_16x16x32_bf16 v[12:15], v[124:127], v[204:207], v[12:15]
	v_mfma_f32_16x16x32_bf16 v[8:11], v[140:143], v[204:207], v[8:11]
	v_mfma_f32_16x16x32_bf16 v[52:55], v[144:147], v[160:163], v[52:55]
	v_mfma_f32_16x16x32_bf16 v[48:51], v[152:155], v[160:163], v[48:51]
	v_mfma_f32_16x16x32_bf16 v[36:39], v[144:147], v[168:171], v[36:39]
	v_mfma_f32_16x16x32_bf16 v[32:35], v[152:155], v[168:171], v[32:35]
	v_mfma_f32_16x16x32_bf16 v[20:23], v[144:147], v[176:179], v[20:23]
	v_mfma_f32_16x16x32_bf16 v[16:19], v[152:155], v[176:179], v[16:19]
	v_mfma_f32_16x16x32_bf16 v[4:7], v[144:147], v[200:203], v[4:7]
	v_mfma_f32_16x16x32_bf16 v[0:3], v[152:155], v[200:203], v[0:3]
	v_mfma_f32_16x16x32_bf16 v[52:55], v[148:151], v[164:167], v[52:55]
	v_mfma_f32_16x16x32_bf16 v[48:51], v[156:159], v[164:167], v[48:51]
	v_mfma_f32_16x16x32_bf16 v[36:39], v[148:151], v[172:175], v[36:39]
	v_mfma_f32_16x16x32_bf16 v[32:35], v[156:159], v[172:175], v[32:35]
	v_mfma_f32_16x16x32_bf16 v[20:23], v[148:151], v[180:183], v[20:23]
	v_mfma_f32_16x16x32_bf16 v[16:19], v[156:159], v[180:183], v[16:19]
	v_mfma_f32_16x16x32_bf16 v[4:7], v[148:151], v[204:207], v[4:7]
	v_mfma_f32_16x16x32_bf16 v[0:3], v[156:159], v[204:207], v[0:3]
	s_setprio 0
	s_barrier
	s_add_i32 s72, 0, 0x18000
	s_add_i32 s73, 0, 0x1c000
	v_add_u32_e32 v140, s72, v220
	v_add_u32_e32 v156, s73, v220
	ds_read_b128 v[112:115], v140
	ds_read_b128 v[124:127], v140 offset:1024
	ds_read_b128 v[136:139], v140 offset:2048
	ds_read_b128 v[140:143], v140 offset:3072
	ds_read_b128 v[144:147], v156
	ds_read_b128 v[148:151], v156 offset:1024
	ds_read_b128 v[152:155], v156 offset:2048
	ds_read_b128 v[156:159], v156 offset:3072
	s_add_u32 s36, s48, 0xb0000
	s_addc_u32 s37, s49, 0
	s_mov_b32 m0, s57
	v_lshl_add_u64 v[226:227], s[36:37], 0, v[184:185]
	ds_read_b128 v[160:163], v225 offset:32768
	ds_read_b128 v[164:167], v225 offset:33792
	ds_read_b128 v[168:171], v225 offset:34816
	ds_read_b128 v[172:175], v225 offset:35840
	ds_read_b128 v[176:179], v225 offset:36864
	ds_read_b128 v[180:183], v225 offset:37888
	ds_read_b128 v[200:203], v225 offset:38912
	ds_read_b128 v[204:207], v225 offset:39936
	global_load_lds_dwordx4 v[226:227], off
	v_lshl_add_u64 v[226:227], s[36:37], 0, v[188:189]
	s_mov_b32 m0, s58
	s_nop 0
	global_load_lds_dwordx4 v[226:227], off
	s_waitcnt vmcnt(8)
	s_waitcnt lgkmcnt(0)
	s_barrier
	s_setprio 1
	s_waitcnt lgkmcnt(0)
	v_mfma_f32_16x16x32_bf16 v[132:135], v[112:115], v[160:163], v[132:135]
	v_mfma_f32_16x16x32_bf16 v[128:131], v[136:139], v[160:163], v[128:131]
	v_mfma_f32_16x16x32_bf16 v[108:111], v[112:115], v[168:171], v[108:111]
	v_mfma_f32_16x16x32_bf16 v[104:107], v[136:139], v[168:171], v[104:107]
	v_mfma_f32_16x16x32_bf16 v[92:95], v[112:115], v[176:179], v[92:95]
	v_mfma_f32_16x16x32_bf16 v[88:91], v[136:139], v[176:179], v[88:91]
	v_mfma_f32_16x16x32_bf16 v[76:79], v[112:115], v[200:203], v[76:79]
	v_mfma_f32_16x16x32_bf16 v[72:75], v[136:139], v[200:203], v[72:75]
	v_mfma_f32_16x16x32_bf16 v[132:135], v[124:127], v[164:167], v[132:135]
	v_mfma_f32_16x16x32_bf16 v[128:131], v[140:143], v[164:167], v[128:131]
	v_mfma_f32_16x16x32_bf16 v[108:111], v[124:127], v[172:175], v[108:111]
	v_mfma_f32_16x16x32_bf16 v[104:107], v[140:143], v[172:175], v[104:107]
	v_mfma_f32_16x16x32_bf16 v[92:95], v[124:127], v[180:183], v[92:95]
	v_mfma_f32_16x16x32_bf16 v[88:91], v[140:143], v[180:183], v[88:91]
	v_mfma_f32_16x16x32_bf16 v[76:79], v[124:127], v[204:207], v[76:79]
	v_mfma_f32_16x16x32_bf16 v[72:75], v[140:143], v[204:207], v[72:75]
	v_mfma_f32_16x16x32_bf16 v[120:123], v[144:147], v[160:163], v[120:123]
	v_mfma_f32_16x16x32_bf16 v[116:119], v[152:155], v[160:163], v[116:119]
	v_mfma_f32_16x16x32_bf16 v[100:103], v[144:147], v[168:171], v[100:103]
	v_mfma_f32_16x16x32_bf16 v[96:99], v[152:155], v[168:171], v[96:99]
	v_mfma_f32_16x16x32_bf16 v[84:87], v[144:147], v[176:179], v[84:87]
	v_mfma_f32_16x16x32_bf16 v[80:83], v[152:155], v[176:179], v[80:83]
	v_mfma_f32_16x16x32_bf16 v[68:71], v[144:147], v[200:203], v[68:71]
	v_mfma_f32_16x16x32_bf16 v[64:67], v[152:155], v[200:203], v[64:67]
	v_mfma_f32_16x16x32_bf16 v[120:123], v[148:151], v[164:167], v[120:123]
	v_mfma_f32_16x16x32_bf16 v[116:119], v[156:159], v[164:167], v[116:119]
	v_mfma_f32_16x16x32_bf16 v[100:103], v[148:151], v[172:175], v[100:103]
	v_mfma_f32_16x16x32_bf16 v[96:99], v[156:159], v[172:175], v[96:99]
	v_mfma_f32_16x16x32_bf16 v[84:87], v[148:151], v[180:183], v[84:87]
	v_mfma_f32_16x16x32_bf16 v[80:83], v[156:159], v[180:183], v[80:83]
	v_mfma_f32_16x16x32_bf16 v[68:71], v[148:151], v[204:207], v[68:71]
	v_mfma_f32_16x16x32_bf16 v[64:67], v[156:159], v[204:207], v[64:67]
	s_setprio 0
	s_barrier
	s_add_i32 s36, s72, s54
	v_lshl_add_u64 v[208:209], v[208:209], 0, s[20:21]
	s_mov_b32 m0, s36
	ds_read_b128 v[160:163], v225 offset:49152
	ds_read_b128 v[164:167], v225 offset:50176
	ds_read_b128 v[168:171], v225 offset:51200
	ds_read_b128 v[172:175], v225 offset:52224
	ds_read_b128 v[176:179], v225 offset:53248
	ds_read_b128 v[180:183], v225 offset:54272
	ds_read_b128 v[200:203], v225 offset:55296
	ds_read_b128 v[204:207], v225 offset:56320
	global_load_lds_dwordx4 v[208:209], off
	s_add_i32 m0, s36, 0x2000
	s_add_u32 s36, s46, 0xb0080
	v_lshl_add_u64 v[208:209], v[210:211], 0, s[20:21]
	s_addc_u32 s37, s47, 0
	s_add_i32 s46, s73, s54
	global_load_lds_dwordx4 v[208:209], off
	v_lshl_add_u64 v[208:209], s[36:37], 0, v[186:187]
	s_mov_b32 m0, s46
	s_nop 0
	global_load_lds_dwordx4 v[208:209], off
	v_lshl_add_u64 v[208:209], s[36:37], 0, v[190:191]
	s_add_i32 m0, s46, 0x2000
	s_nop 0
	global_load_lds_dwordx4 v[208:209], off
	v_lshl_add_u64 v[208:209], v[212:213], 0, s[20:21]
	s_mov_b32 m0, s60
	s_nop 0
	global_load_lds_dwordx4 v[208:209], off
	v_lshl_add_u64 v[208:209], v[214:215], 0, s[20:21]
	s_mov_b32 m0, s61
	s_nop 0
	global_load_lds_dwordx4 v[208:209], off
	s_waitcnt vmcnt(8)
	s_waitcnt lgkmcnt(0)
	s_barrier
	s_setprio 1
	s_waitcnt lgkmcnt(0)
	v_mfma_f32_16x16x32_bf16 v[60:63], v[112:115], v[160:163], v[60:63]
	v_mfma_f32_16x16x32_bf16 v[56:59], v[136:139], v[160:163], v[56:59]
	v_mfma_f32_16x16x32_bf16 v[44:47], v[112:115], v[168:171], v[44:47]
	v_mfma_f32_16x16x32_bf16 v[40:43], v[136:139], v[168:171], v[40:43]
	v_mfma_f32_16x16x32_bf16 v[28:31], v[112:115], v[176:179], v[28:31]
	v_mfma_f32_16x16x32_bf16 v[24:27], v[136:139], v[176:179], v[24:27]
	v_mfma_f32_16x16x32_bf16 v[12:15], v[112:115], v[200:203], v[12:15]
	v_mfma_f32_16x16x32_bf16 v[8:11], v[136:139], v[200:203], v[8:11]
	v_mfma_f32_16x16x32_bf16 v[60:63], v[124:127], v[164:167], v[60:63]
	v_mfma_f32_16x16x32_bf16 v[56:59], v[140:143], v[164:167], v[56:59]
	v_mfma_f32_16x16x32_bf16 v[44:47], v[124:127], v[172:175], v[44:47]
	v_mfma_f32_16x16x32_bf16 v[40:43], v[140:143], v[172:175], v[40:43]
	v_mfma_f32_16x16x32_bf16 v[28:31], v[124:127], v[180:183], v[28:31]
	v_mfma_f32_16x16x32_bf16 v[24:27], v[140:143], v[180:183], v[24:27]
	v_mfma_f32_16x16x32_bf16 v[12:15], v[124:127], v[204:207], v[12:15]
	v_mfma_f32_16x16x32_bf16 v[8:11], v[140:143], v[204:207], v[8:11]
	v_mfma_f32_16x16x32_bf16 v[52:55], v[144:147], v[160:163], v[52:55]
	v_mfma_f32_16x16x32_bf16 v[48:51], v[152:155], v[160:163], v[48:51]
	v_mfma_f32_16x16x32_bf16 v[36:39], v[144:147], v[168:171], v[36:39]
	v_mfma_f32_16x16x32_bf16 v[32:35], v[152:155], v[168:171], v[32:35]
	v_mfma_f32_16x16x32_bf16 v[20:23], v[144:147], v[176:179], v[20:23]
	v_mfma_f32_16x16x32_bf16 v[16:19], v[152:155], v[176:179], v[16:19]
	v_mfma_f32_16x16x32_bf16 v[4:7], v[144:147], v[200:203], v[4:7]
	v_mfma_f32_16x16x32_bf16 v[0:3], v[152:155], v[200:203], v[0:3]
	v_mfma_f32_16x16x32_bf16 v[52:55], v[148:151], v[164:167], v[52:55]
	v_mfma_f32_16x16x32_bf16 v[48:51], v[156:159], v[164:167], v[48:51]
	v_mfma_f32_16x16x32_bf16 v[36:39], v[148:151], v[172:175], v[36:39]
	v_mfma_f32_16x16x32_bf16 v[32:35], v[156:159], v[172:175], v[32:35]
	v_mfma_f32_16x16x32_bf16 v[20:23], v[148:151], v[180:183], v[20:23]
	v_mfma_f32_16x16x32_bf16 v[16:19], v[156:159], v[180:183], v[16:19]
	v_mfma_f32_16x16x32_bf16 v[4:7], v[148:151], v[204:207], v[4:7]
	v_mfma_f32_16x16x32_bf16 v[0:3], v[156:159], v[204:207], v[0:3]
	s_setprio 0
	s_barrier
	s_add_i32 s71, s71, 2
	s_add_u32 s69, s69, 0x100
	s_addc_u32 s70, s70, 0
	s_cmp_gt_u32 s71, 41
	s_mov_b64 s[36:37], s[38:39]
	s_cbranch_scc0 .LBB0_1151
	s_and_b64 vcc, exec, s[22:23]
	s_cbranch_vccz .LBB0_1154
	s_barrier
